# residual-GEMM epilogue software-pipelined: the x rows of the next 32-row block are loaded into the dead accumulators of the block just updated, before its row-sum reductions
# baseline (speedup 1.0000x reference)
.Lhw_outproj_loop:
	v_mfma_f32_32x32x16_bf16 v[2:17], v[130:133], v[220:223], v[2:17]
	s_add_u32 m0, s65, 0x4000
	s_nop 0
	global_load_lds_dwordx4 v242, s[18:19]
	v_mfma_f32_32x32x16_bf16 v[34:49], v[146:149], v[220:223], v[34:49]
	s_add_u32 m0, s65, 0x5000
	ds_read_b128 v[220:223], v158 offset:16
	global_load_lds_dwordx4 v243, s[18:19]
	v_mfma_f32_32x32x16_bf16 v[2:17], v[134:137], v[224:227], v[2:17]
	s_add_u32 s62, s62, 128
	s_addc_u32 s63, s63, 0
	s_add_u32 s66, s66, 128
	s_addc_u32 s67, s67, 0
	v_mfma_f32_32x32x16_bf16 v[34:49], v[150:153], v[224:227], v[34:49]
	s_add_u32 m0, s65, 0x6000
	ds_read_b128 v[224:227], v159 offset:16
	global_load_lds_dwordx4 v160, s[62:63]
	v_mfma_f32_32x32x16_bf16 v[2:17], v[138:141], v[228:231], v[2:17]
	s_add_u32 m0, s65, 0x7000
	s_nop 0
	global_load_lds_dwordx4 v161, s[62:63]
	v_mfma_f32_32x32x16_bf16 v[34:49], v[212:215], v[228:231], v[34:49]
	s_add_u32 m0, s65, 0x8000
	ds_read_b128 v[228:231], v236 offset:16
	global_load_lds_dwordx4 v160, s[66:67]
	v_mfma_f32_32x32x16_bf16 v[2:17], v[142:145], v[232:235], v[2:17]
	s_add_u32 m0, s65, 0x9000
	s_nop 0
	global_load_lds_dwordx4 v161, s[66:67]
	v_mfma_f32_32x32x16_bf16 v[34:49], v[216:219], v[232:235], v[34:49]
	s_add_u32 m0, s65, 0xa000
	ds_read_b128 v[232:235], v237 offset:16
	global_load_lds_dwordx4 v242, s[66:67]
	s_waitcnt lgkmcnt(3)
	v_mfma_f32_32x32x16_bf16 v[18:33], v[130:133], v[220:223], v[18:33]
	s_add_u32 m0, s65, 0xb000
	s_nop 0
	global_load_lds_dwordx4 v243, s[66:67]
	v_mfma_f32_32x32x16_bf16 v[50:65], v[146:149], v[220:223], v[50:65]
	ds_read_b128 v[220:223], v158 offset:8208
	s_waitcnt lgkmcnt(3)
	v_mfma_f32_32x32x16_bf16 v[18:33], v[134:137], v[224:227], v[18:33]
	v_mfma_f32_32x32x16_bf16 v[50:65], v[150:153], v[224:227], v[50:65]
	ds_read_b128 v[224:227], v159 offset:8208
	s_waitcnt lgkmcnt(3)
	v_mfma_f32_32x32x16_bf16 v[18:33], v[138:141], v[228:231], v[18:33]
	v_mfma_f32_32x32x16_bf16 v[50:65], v[212:215], v[228:231], v[50:65]
	ds_read_b128 v[228:231], v236 offset:8208
	s_waitcnt lgkmcnt(3)
	v_mfma_f32_32x32x16_bf16 v[18:33], v[142:145], v[232:235], v[18:33]
	v_mfma_f32_32x32x16_bf16 v[50:65], v[216:219], v[232:235], v[50:65]
	ds_read_b128 v[232:235], v237 offset:8208
	s_waitcnt vmcnt(0) lgkmcnt(0)
	s_barrier
	v_mfma_f32_32x32x16_bf16 v[66:81], v[130:133], v[220:223], v[66:81]
	s_add_u32 s18, s18, 128
	s_addc_u32 s19, s19, 0
	v_mfma_f32_32x32x16_bf16 v[98:113], v[146:149], v[220:223], v[98:113]
	s_add_u32 m0, s65, 0x0
	ds_read_b128 v[220:223], v158 offset:16400
	global_load_lds_dwordx4 v242, s[62:63]
	v_mfma_f32_32x32x16_bf16 v[66:81], v[134:137], v[224:227], v[66:81]
	s_add_u32 m0, s65, 0x1000
	s_nop 0
	global_load_lds_dwordx4 v243, s[62:63]
	v_mfma_f32_32x32x16_bf16 v[98:113], v[150:153], v[224:227], v[98:113]
	s_add_u32 m0, s65, 0x2000
	ds_read_b128 v[224:227], v159 offset:16400
	global_load_lds_dwordx4 v160, s[18:19]
	v_mfma_f32_32x32x16_bf16 v[66:81], v[138:141], v[228:231], v[66:81]
	s_add_u32 m0, s65, 0x3000
	s_nop 0
	global_load_lds_dwordx4 v161, s[18:19]
	v_mfma_f32_32x32x16_bf16 v[98:113], v[212:215], v[228:231], v[98:113]
	ds_read_b128 v[228:231], v236 offset:16400
	v_mfma_f32_32x32x16_bf16 v[66:81], v[142:145], v[232:235], v[66:81]
	v_mfma_f32_32x32x16_bf16 v[98:113], v[216:219], v[232:235], v[98:113]
	ds_read_b128 v[232:235], v237 offset:16400
	s_waitcnt lgkmcnt(3)
	v_mfma_f32_32x32x16_bf16 v[82:97], v[130:133], v[220:223], v[82:97]
	ds_read_b128 v[130:133], v154 offset:32784
	v_mfma_f32_32x32x16_bf16 v[114:129], v[146:149], v[220:223], v[114:129]
	ds_read_b128 v[220:223], v158 offset:24592
	ds_read_b128 v[146:149], v154 offset:40976
	s_waitcnt lgkmcnt(5)
	v_mfma_f32_32x32x16_bf16 v[82:97], v[134:137], v[224:227], v[82:97]
	ds_read_b128 v[134:137], v155 offset:32784
	v_mfma_f32_32x32x16_bf16 v[114:129], v[150:153], v[224:227], v[114:129]
	ds_read_b128 v[224:227], v159 offset:24592
	ds_read_b128 v[150:153], v155 offset:40976
	s_waitcnt lgkmcnt(7)
	v_mfma_f32_32x32x16_bf16 v[82:97], v[138:141], v[228:231], v[82:97]
	ds_read_b128 v[138:141], v156 offset:32784
	v_mfma_f32_32x32x16_bf16 v[114:129], v[212:215], v[228:231], v[114:129]
	ds_read_b128 v[228:231], v236 offset:24592
	ds_read_b128 v[212:215], v156 offset:40976
	s_waitcnt lgkmcnt(9)
	v_mfma_f32_32x32x16_bf16 v[82:97], v[142:145], v[232:235], v[82:97]
	ds_read_b128 v[142:145], v157 offset:32784
	v_mfma_f32_32x32x16_bf16 v[114:129], v[216:219], v[232:235], v[114:129]
	ds_read_b128 v[232:235], v237 offset:24592
	ds_read_b128 v[216:219], v157 offset:40976
	s_waitcnt vmcnt(0) lgkmcnt(0)
	s_barrier
	s_sub_u32 s59, s59, 1
	s_cmp_lg_u32 s59, 0
	s_cbranch_scc1 .Lhw_outproj_loop
	v_mfma_f32_32x32x16_bf16 v[2:17], v[130:133], v[220:223], v[2:17]
	s_add_u32 m0, s65, 0x4000
	s_nop 0
	global_load_lds_dwordx4 v242, s[18:19]
	v_mfma_f32_32x32x16_bf16 v[34:49], v[146:149], v[220:223], v[34:49]
	s_add_u32 m0, s65, 0x5000
	ds_read_b128 v[220:223], v158 offset:16
	global_load_lds_dwordx4 v243, s[18:19]
	v_mfma_f32_32x32x16_bf16 v[2:17], v[134:137], v[224:227], v[2:17]
	v_mfma_f32_32x32x16_bf16 v[34:49], v[150:153], v[224:227], v[34:49]
	ds_read_b128 v[224:227], v159 offset:16
	v_mfma_f32_32x32x16_bf16 v[2:17], v[138:141], v[228:231], v[2:17]
	v_mfma_f32_32x32x16_bf16 v[34:49], v[212:215], v[228:231], v[34:49]
	ds_read_b128 v[228:231], v236 offset:16
	v_mfma_f32_32x32x16_bf16 v[2:17], v[142:145], v[232:235], v[2:17]
	v_mfma_f32_32x32x16_bf16 v[34:49], v[216:219], v[232:235], v[34:49]
	ds_read_b128 v[232:235], v237 offset:16
	s_waitcnt lgkmcnt(3)
	v_mfma_f32_32x32x16_bf16 v[18:33], v[130:133], v[220:223], v[18:33]
	v_mfma_f32_32x32x16_bf16 v[50:65], v[146:149], v[220:223], v[50:65]
	ds_read_b128 v[220:223], v158 offset:8208
	s_waitcnt lgkmcnt(3)
	v_mfma_f32_32x32x16_bf16 v[18:33], v[134:137], v[224:227], v[18:33]
	v_mfma_f32_32x32x16_bf16 v[50:65], v[150:153], v[224:227], v[50:65]
	ds_read_b128 v[224:227], v159 offset:8208
	s_waitcnt lgkmcnt(3)
	v_mfma_f32_32x32x16_bf16 v[18:33], v[138:141], v[228:231], v[18:33]
	v_mfma_f32_32x32x16_bf16 v[50:65], v[212:215], v[228:231], v[50:65]
	ds_read_b128 v[228:231], v236 offset:8208
	s_waitcnt lgkmcnt(3)
	v_mfma_f32_32x32x16_bf16 v[18:33], v[142:145], v[232:235], v[18:33]
	v_mfma_f32_32x32x16_bf16 v[50:65], v[216:219], v[232:235], v[50:65]
	ds_read_b128 v[232:235], v237 offset:8208
	s_waitcnt vmcnt(0) lgkmcnt(0)
	s_barrier
	v_mfma_f32_32x32x16_bf16 v[66:81], v[130:133], v[220:223], v[66:81]
	v_mfma_f32_32x32x16_bf16 v[98:113], v[146:149], v[220:223], v[98:113]
	ds_read_b128 v[220:223], v158 offset:16400
	v_mfma_f32_32x32x16_bf16 v[66:81], v[134:137], v[224:227], v[66:81]
	v_mfma_f32_32x32x16_bf16 v[98:113], v[150:153], v[224:227], v[98:113]
	ds_read_b128 v[224:227], v159 offset:16400
	v_mfma_f32_32x32x16_bf16 v[66:81], v[138:141], v[228:231], v[66:81]
	v_mfma_f32_32x32x16_bf16 v[98:113], v[212:215], v[228:231], v[98:113]
	ds_read_b128 v[228:231], v236 offset:16400
	v_mfma_f32_32x32x16_bf16 v[66:81], v[142:145], v[232:235], v[66:81]
	v_mfma_f32_32x32x16_bf16 v[98:113], v[216:219], v[232:235], v[98:113]
	ds_read_b128 v[232:235], v237 offset:16400
	s_waitcnt lgkmcnt(3)
	v_mfma_f32_32x32x16_bf16 v[82:97], v[130:133], v[220:223], v[82:97]
	v_mfma_f32_32x32x16_bf16 v[114:129], v[146:149], v[220:223], v[114:129]
	s_waitcnt lgkmcnt(2)
	v_mfma_f32_32x32x16_bf16 v[82:97], v[134:137], v[224:227], v[82:97]
	v_mfma_f32_32x32x16_bf16 v[114:129], v[150:153], v[224:227], v[114:129]
	s_waitcnt lgkmcnt(1)
	v_mfma_f32_32x32x16_bf16 v[82:97], v[138:141], v[228:231], v[82:97]
	v_mfma_f32_32x32x16_bf16 v[114:129], v[212:215], v[228:231], v[114:129]
	s_waitcnt lgkmcnt(0)
	v_mfma_f32_32x32x16_bf16 v[82:97], v[142:145], v[232:235], v[82:97]
	v_mfma_f32_32x32x16_bf16 v[114:129], v[216:219], v[232:235], v[114:129]
	s_nop 7
	s_nop 7
	s_sub_i32 s2, s6, 0x1000
	s_ashr_i32 s2, s2, 11
	s_add_i32 s2, s2, 1
	s_max_i32 s2, s2, 0
	v_readlane_b32 s17, v246, 28
	s_nop 0
	s_add_i32 s2, s2, s17
	s_mul_i32 s2, s2, 0x9000
	s_lshl_b32 s17, s15, 2
	s_add_u32 s2, s2, s17
	s_add_u32 s60, s8, s2
	s_addc_u32 s61, s9, 0
	s_lshr_b32 s2, s15, 7
	s_mul_i32 s2, s2, 0x18000
	s_lshl_b32 s20, s6, 2
	s_add_u32 s2, s2, s20
	s_add_u32 s10, s44, s2
	s_addc_u32 s11, s45, 0
	s_lshl_b32 s2, s6, 12
	s_add_u32 s2, s2, s17
	s_add_u32 s48, s40, s2
	s_addc_u32 s49, s41, 0
	global_load_dword v175, v166, s[60:61]
	global_load_dword v176, v166, s[60:61] offset:128
	global_load_dword v130, v162, s[48:49]
	global_load_dword v212, v162, s[48:49] offset:128
	global_load_dword v131, v163, s[48:49]
	global_load_dword v213, v163, s[48:49] offset:128
	global_load_dword v132, v164, s[48:49]
	global_load_dword v214, v164, s[48:49] offset:128
	global_load_dword v133, v165, s[48:49]
	global_load_dword v215, v165, s[48:49] offset:128
	s_add_u32 s48, s48, 0x8000
	s_addc_u32 s49, s49, 0
	global_load_dword v134, v162, s[48:49]
	global_load_dword v216, v162, s[48:49] offset:128
	global_load_dword v135, v163, s[48:49]
	global_load_dword v217, v163, s[48:49] offset:128
	global_load_dword v136, v164, s[48:49]
	global_load_dword v218, v164, s[48:49] offset:128
	global_load_dword v137, v165, s[48:49]
	global_load_dword v219, v165, s[48:49] offset:128
	s_add_u32 s48, s48, 0x8000
	s_addc_u32 s49, s49, 0
	global_load_dword v138, v162, s[48:49]
	global_load_dword v220, v162, s[48:49] offset:128
	global_load_dword v139, v163, s[48:49]
	global_load_dword v221, v163, s[48:49] offset:128
	global_load_dword v140, v164, s[48:49]
	global_load_dword v222, v164, s[48:49] offset:128
	global_load_dword v141, v165, s[48:49]
	global_load_dword v223, v165, s[48:49] offset:128
	s_add_u32 s48, s48, 0x8000
	s_addc_u32 s49, s49, 0
	global_load_dword v142, v162, s[48:49]
	global_load_dword v224, v162, s[48:49] offset:128
	global_load_dword v143, v163, s[48:49]
	global_load_dword v225, v163, s[48:49] offset:128
	global_load_dword v144, v164, s[48:49]
	global_load_dword v226, v164, s[48:49] offset:128
	global_load_dword v145, v165, s[48:49]
	global_load_dword v227, v165, s[48:49] offset:128
	s_sub_u32 s48, s48, 0x18000
	s_subb_u32 s49, s49, 0
	s_waitcnt vmcnt(32)
	s_waitcnt vmcnt(30)
	v_fmac_f32_e32 v130, v2, v175
	v_fmac_f32_e32 v212, v18, v176
	global_store_dword v162, v130, s[48:49]
	global_store_dword v162, v212, s[48:49] offset:128
	s_waitcnt vmcnt(30)
	v_fmac_f32_e32 v131, v3, v175
	v_fmac_f32_e32 v213, v19, v176
	global_store_dword v163, v131, s[48:49]
	global_store_dword v163, v213, s[48:49] offset:128
	s_waitcnt vmcnt(30)
	v_fmac_f32_e32 v132, v4, v175
	v_fmac_f32_e32 v214, v20, v176
	global_store_dword v164, v132, s[48:49]
	global_store_dword v164, v214, s[48:49] offset:128
	s_waitcnt vmcnt(30)
	v_fmac_f32_e32 v133, v5, v175
	v_fmac_f32_e32 v215, v21, v176
	global_store_dword v165, v133, s[48:49]
	global_store_dword v165, v215, s[48:49] offset:128
	s_add_u32 s48, s48, 0x8000
	s_addc_u32 s49, s49, 0
	s_waitcnt vmcnt(30)
	v_fmac_f32_e32 v134, v6, v175
	v_fmac_f32_e32 v216, v22, v176
	global_store_dword v162, v134, s[48:49]
	global_store_dword v162, v216, s[48:49] offset:128
	s_waitcnt vmcnt(30)
	v_fmac_f32_e32 v135, v7, v175
	v_fmac_f32_e32 v217, v23, v176
	global_store_dword v163, v135, s[48:49]
	global_store_dword v163, v217, s[48:49] offset:128
	s_waitcnt vmcnt(30)
	v_fmac_f32_e32 v136, v8, v175
	v_fmac_f32_e32 v218, v24, v176
	global_store_dword v164, v136, s[48:49]
	global_store_dword v164, v218, s[48:49] offset:128
	s_waitcnt vmcnt(30)
	v_fmac_f32_e32 v137, v9, v175
	v_fmac_f32_e32 v219, v25, v176
	global_store_dword v165, v137, s[48:49]
	global_store_dword v165, v219, s[48:49] offset:128
	s_add_u32 s48, s48, 0x8000
	s_addc_u32 s49, s49, 0
	s_waitcnt vmcnt(30)
	v_fmac_f32_e32 v138, v10, v175
	v_fmac_f32_e32 v220, v26, v176
	global_store_dword v162, v138, s[48:49]
	global_store_dword v162, v220, s[48:49] offset:128
	s_waitcnt vmcnt(30)
	v_fmac_f32_e32 v139, v11, v175
	v_fmac_f32_e32 v221, v27, v176
	global_store_dword v163, v139, s[48:49]
	global_store_dword v163, v221, s[48:49] offset:128
	s_waitcnt vmcnt(30)
	v_fmac_f32_e32 v140, v12, v175
	v_fmac_f32_e32 v222, v28, v176
	global_store_dword v164, v140, s[48:49]
	global_store_dword v164, v222, s[48:49] offset:128
	s_waitcnt vmcnt(30)
	v_fmac_f32_e32 v141, v13, v175
	v_fmac_f32_e32 v223, v29, v176
	global_store_dword v165, v141, s[48:49]
	global_store_dword v165, v223, s[48:49] offset:128
	s_add_u32 s48, s48, 0x8000
	s_addc_u32 s49, s49, 0
	s_waitcnt vmcnt(30)
	v_fmac_f32_e32 v142, v14, v175
	v_fmac_f32_e32 v224, v30, v176
	global_store_dword v162, v142, s[48:49]
	global_store_dword v162, v224, s[48:49] offset:128
	s_waitcnt vmcnt(30)
	v_fmac_f32_e32 v143, v15, v175
	v_fmac_f32_e32 v225, v31, v176
	global_store_dword v163, v143, s[48:49]
	global_store_dword v163, v225, s[48:49] offset:128
	s_waitcnt vmcnt(30)
	v_fmac_f32_e32 v144, v16, v175
	v_fmac_f32_e32 v226, v32, v176
	global_store_dword v164, v144, s[48:49]
	global_store_dword v164, v226, s[48:49] offset:128
	s_waitcnt vmcnt(30)
	v_fmac_f32_e32 v145, v17, v175
	v_fmac_f32_e32 v227, v33, v176
	global_store_dword v165, v145, s[48:49]
	global_store_dword v165, v227, s[48:49] offset:128
	s_sub_u32 s48, s48, 0x18000
	s_subb_u32 s49, s49, 0
	s_add_u32 s48, s48, 0x20000
	s_addc_u32 s49, s49, 0
	global_load_dword v2, v162, s[48:49]
	global_load_dword v18, v162, s[48:49] offset:128
	global_load_dword v3, v163, s[48:49]
	global_load_dword v19, v163, s[48:49] offset:128
	global_load_dword v4, v164, s[48:49]
	global_load_dword v20, v164, s[48:49] offset:128
	global_load_dword v5, v165, s[48:49]
	global_load_dword v21, v165, s[48:49] offset:128
	s_add_u32 s48, s48, 0x8000
	s_addc_u32 s49, s49, 0
	global_load_dword v6, v162, s[48:49]
	global_load_dword v22, v162, s[48:49] offset:128
	global_load_dword v7, v163, s[48:49]
	global_load_dword v23, v163, s[48:49] offset:128
	global_load_dword v8, v164, s[48:49]
	global_load_dword v24, v164, s[48:49] offset:128
	global_load_dword v9, v165, s[48:49]
	global_load_dword v25, v165, s[48:49] offset:128
	s_add_u32 s48, s48, 0x8000
	s_addc_u32 s49, s49, 0
	global_load_dword v10, v162, s[48:49]
	global_load_dword v26, v162, s[48:49] offset:128
	global_load_dword v11, v163, s[48:49]
	global_load_dword v27, v163, s[48:49] offset:128
	global_load_dword v12, v164, s[48:49]
	global_load_dword v28, v164, s[48:49] offset:128
	global_load_dword v13, v165, s[48:49]
	global_load_dword v29, v165, s[48:49] offset:128
	s_add_u32 s48, s48, 0x8000
	s_addc_u32 s49, s49, 0
	global_load_dword v14, v162, s[48:49]
	global_load_dword v30, v162, s[48:49] offset:128
	global_load_dword v15, v163, s[48:49]
	global_load_dword v31, v163, s[48:49] offset:128
	global_load_dword v16, v164, s[48:49]
	global_load_dword v32, v164, s[48:49] offset:128
	global_load_dword v17, v165, s[48:49]
	global_load_dword v33, v165, s[48:49] offset:128
	s_sub_u32 s48, s48, 0x18000
	s_subb_u32 s49, s49, 0
	v_mul_f32_e32 v130, v130, v130
	v_fmac_f32_e32 v130, v212, v212
	v_mul_f32_e32 v131, v131, v131
	v_fmac_f32_e32 v131, v213, v213
	v_mul_f32_e32 v132, v132, v132
	v_fmac_f32_e32 v132, v214, v214
	v_mul_f32_e32 v133, v133, v133
	v_fmac_f32_e32 v133, v215, v215
	v_mul_f32_e32 v134, v134, v134
	v_fmac_f32_e32 v134, v216, v216
	v_mul_f32_e32 v135, v135, v135
	v_fmac_f32_e32 v135, v217, v217
	v_mul_f32_e32 v136, v136, v136
	v_fmac_f32_e32 v136, v218, v218
	v_mul_f32_e32 v137, v137, v137
	v_fmac_f32_e32 v137, v219, v219
	v_mul_f32_e32 v138, v138, v138
	v_fmac_f32_e32 v138, v220, v220
	v_mul_f32_e32 v139, v139, v139
	v_fmac_f32_e32 v139, v221, v221
	v_mul_f32_e32 v140, v140, v140
	v_fmac_f32_e32 v140, v222, v222
	v_mul_f32_e32 v141, v141, v141
	v_fmac_f32_e32 v141, v223, v223
	v_mul_f32_e32 v142, v142, v142
	v_fmac_f32_e32 v142, v224, v224
	v_mul_f32_e32 v143, v143, v143
	v_fmac_f32_e32 v143, v225, v225
	v_mul_f32_e32 v144, v144, v144
	v_fmac_f32_e32 v144, v226, v226
	v_mul_f32_e32 v145, v145, v145
	v_fmac_f32_e32 v145, v227, v227
	s_waitcnt lgkmcnt(0)
	ds_bpermute_b32 v212, v168, v130
	ds_bpermute_b32 v213, v168, v131
	ds_bpermute_b32 v214, v168, v132
	ds_bpermute_b32 v215, v168, v133
	ds_bpermute_b32 v216, v168, v134
	ds_bpermute_b32 v217, v168, v135
	ds_bpermute_b32 v218, v168, v136
	ds_bpermute_b32 v219, v168, v137
	s_waitcnt lgkmcnt(7)
	v_add_f32_e32 v130, v130, v212
	s_waitcnt lgkmcnt(6)
	v_add_f32_e32 v131, v131, v213
	s_waitcnt lgkmcnt(5)
	v_add_f32_e32 v132, v132, v214
	s_waitcnt lgkmcnt(4)
	v_add_f32_e32 v133, v133, v215
	s_waitcnt lgkmcnt(3)
	v_add_f32_e32 v134, v134, v216
	s_waitcnt lgkmcnt(2)
	v_add_f32_e32 v135, v135, v217
	s_waitcnt lgkmcnt(1)
	v_add_f32_e32 v136, v136, v218
	s_waitcnt lgkmcnt(0)
	v_add_f32_e32 v137, v137, v219
	ds_bpermute_b32 v212, v169, v130
	ds_bpermute_b32 v213, v169, v131
	ds_bpermute_b32 v214, v169, v132
	ds_bpermute_b32 v215, v169, v133
	ds_bpermute_b32 v216, v169, v134
	ds_bpermute_b32 v217, v169, v135
	ds_bpermute_b32 v218, v169, v136
	ds_bpermute_b32 v219, v169, v137
	s_waitcnt lgkmcnt(7)
	v_add_f32_e32 v130, v130, v212
	s_waitcnt lgkmcnt(6)
	v_add_f32_e32 v131, v131, v213
	s_waitcnt lgkmcnt(5)
	v_add_f32_e32 v132, v132, v214
	s_waitcnt lgkmcnt(4)
	v_add_f32_e32 v133, v133, v215
	s_waitcnt lgkmcnt(3)
	v_add_f32_e32 v134, v134, v216
	s_waitcnt lgkmcnt(2)
	v_add_f32_e32 v135, v135, v217
	s_waitcnt lgkmcnt(1)
	v_add_f32_e32 v136, v136, v218
	s_waitcnt lgkmcnt(0)
	v_add_f32_e32 v137, v137, v219
	ds_bpermute_b32 v212, v171, v130
	ds_bpermute_b32 v213, v171, v131
	ds_bpermute_b32 v214, v171, v132
	ds_bpermute_b32 v215, v171, v133
	ds_bpermute_b32 v216, v171, v134
	ds_bpermute_b32 v217, v171, v135
	ds_bpermute_b32 v218, v171, v136
	ds_bpermute_b32 v219, v171, v137
	s_waitcnt lgkmcnt(7)
	v_add_f32_e32 v130, v130, v212
	s_waitcnt lgkmcnt(6)
	v_add_f32_e32 v131, v131, v213
	s_waitcnt lgkmcnt(5)
	v_add_f32_e32 v132, v132, v214
	s_waitcnt lgkmcnt(4)
	v_add_f32_e32 v133, v133, v215
	s_waitcnt lgkmcnt(3)
	v_add_f32_e32 v134, v134, v216
	s_waitcnt lgkmcnt(2)
	v_add_f32_e32 v135, v135, v217
	s_waitcnt lgkmcnt(1)
	v_add_f32_e32 v136, v136, v218
	s_waitcnt lgkmcnt(0)
	v_add_f32_e32 v137, v137, v219
	ds_bpermute_b32 v212, v172, v130
	ds_bpermute_b32 v213, v172, v131
	ds_bpermute_b32 v214, v172, v132
	ds_bpermute_b32 v215, v172, v133
	ds_bpermute_b32 v216, v172, v134
	ds_bpermute_b32 v217, v172, v135
	ds_bpermute_b32 v218, v172, v136
	ds_bpermute_b32 v219, v172, v137
	s_waitcnt lgkmcnt(7)
	v_add_f32_e32 v130, v130, v212
	s_waitcnt lgkmcnt(6)
	v_add_f32_e32 v131, v131, v213
	s_waitcnt lgkmcnt(5)
	v_add_f32_e32 v132, v132, v214
	s_waitcnt lgkmcnt(4)
	v_add_f32_e32 v133, v133, v215
	s_waitcnt lgkmcnt(3)
	v_add_f32_e32 v134, v134, v216
	s_waitcnt lgkmcnt(2)
	v_add_f32_e32 v135, v135, v217
	s_waitcnt lgkmcnt(1)
	v_add_f32_e32 v136, v136, v218
	s_waitcnt lgkmcnt(0)
	v_add_f32_e32 v137, v137, v219
	ds_bpermute_b32 v212, v173, v130
	ds_bpermute_b32 v213, v173, v131
	ds_bpermute_b32 v214, v173, v132
	ds_bpermute_b32 v215, v173, v133
	ds_bpermute_b32 v216, v173, v134
	ds_bpermute_b32 v217, v173, v135
	ds_bpermute_b32 v218, v173, v136
	ds_bpermute_b32 v219, v173, v137
	s_waitcnt lgkmcnt(7)
	v_add_f32_e32 v130, v130, v212
	s_waitcnt lgkmcnt(6)
	v_add_f32_e32 v131, v131, v213
	s_waitcnt lgkmcnt(5)
	v_add_f32_e32 v132, v132, v214
	s_waitcnt lgkmcnt(4)
	v_add_f32_e32 v133, v133, v215
	s_waitcnt lgkmcnt(3)
	v_add_f32_e32 v134, v134, v216
	s_waitcnt lgkmcnt(2)
	v_add_f32_e32 v135, v135, v217
	s_waitcnt lgkmcnt(1)
	v_add_f32_e32 v136, v136, v218
	s_waitcnt lgkmcnt(0)
	v_add_f32_e32 v137, v137, v219
	ds_bpermute_b32 v220, v168, v138
	ds_bpermute_b32 v221, v168, v139
	ds_bpermute_b32 v222, v168, v140
	ds_bpermute_b32 v223, v168, v141
	ds_bpermute_b32 v224, v168, v142
	ds_bpermute_b32 v225, v168, v143
	ds_bpermute_b32 v226, v168, v144
	ds_bpermute_b32 v227, v168, v145
	s_waitcnt lgkmcnt(7)
	v_add_f32_e32 v138, v138, v220
	s_waitcnt lgkmcnt(6)
	v_add_f32_e32 v139, v139, v221
	s_waitcnt lgkmcnt(5)
	v_add_f32_e32 v140, v140, v222
	s_waitcnt lgkmcnt(4)
	v_add_f32_e32 v141, v141, v223
	s_waitcnt lgkmcnt(3)
	v_add_f32_e32 v142, v142, v224
	s_waitcnt lgkmcnt(2)
	v_add_f32_e32 v143, v143, v225
	s_waitcnt lgkmcnt(1)
	v_add_f32_e32 v144, v144, v226
	s_waitcnt lgkmcnt(0)
	v_add_f32_e32 v145, v145, v227
	ds_bpermute_b32 v220, v169, v138
	ds_bpermute_b32 v221, v169, v139
	ds_bpermute_b32 v222, v169, v140
	ds_bpermute_b32 v223, v169, v141
	ds_bpermute_b32 v224, v169, v142
	ds_bpermute_b32 v225, v169, v143
	ds_bpermute_b32 v226, v169, v144
	ds_bpermute_b32 v227, v169, v145
	s_waitcnt lgkmcnt(7)
	v_add_f32_e32 v138, v138, v220
	s_waitcnt lgkmcnt(6)
	v_add_f32_e32 v139, v139, v221
	s_waitcnt lgkmcnt(5)
	v_add_f32_e32 v140, v140, v222
	s_waitcnt lgkmcnt(4)
	v_add_f32_e32 v141, v141, v223
	s_waitcnt lgkmcnt(3)
	v_add_f32_e32 v142, v142, v224
	s_waitcnt lgkmcnt(2)
	v_add_f32_e32 v143, v143, v225
	s_waitcnt lgkmcnt(1)
	v_add_f32_e32 v144, v144, v226
	s_waitcnt lgkmcnt(0)
	v_add_f32_e32 v145, v145, v227
	ds_bpermute_b32 v220, v171, v138
	ds_bpermute_b32 v221, v171, v139
	ds_bpermute_b32 v222, v171, v140
	ds_bpermute_b32 v223, v171, v141
	ds_bpermute_b32 v224, v171, v142
	ds_bpermute_b32 v225, v171, v143
	ds_bpermute_b32 v226, v171, v144
	ds_bpermute_b32 v227, v171, v145
	s_waitcnt lgkmcnt(7)
	v_add_f32_e32 v138, v138, v220
	s_waitcnt lgkmcnt(6)
	v_add_f32_e32 v139, v139, v221
	s_waitcnt lgkmcnt(5)
	v_add_f32_e32 v140, v140, v222
	s_waitcnt lgkmcnt(4)
	v_add_f32_e32 v141, v141, v223
	s_waitcnt lgkmcnt(3)
	v_add_f32_e32 v142, v142, v224
	s_waitcnt lgkmcnt(2)
	v_add_f32_e32 v143, v143, v225
	s_waitcnt lgkmcnt(1)
	v_add_f32_e32 v144, v144, v226
	s_waitcnt lgkmcnt(0)
	v_add_f32_e32 v145, v145, v227
	ds_bpermute_b32 v220, v172, v138
	ds_bpermute_b32 v221, v172, v139
	ds_bpermute_b32 v222, v172, v140
	ds_bpermute_b32 v223, v172, v141
	ds_bpermute_b32 v224, v172, v142
	ds_bpermute_b32 v225, v172, v143
	ds_bpermute_b32 v226, v172, v144
	ds_bpermute_b32 v227, v172, v145
	s_waitcnt lgkmcnt(7)
	v_add_f32_e32 v138, v138, v220
	s_waitcnt lgkmcnt(6)
	v_add_f32_e32 v139, v139, v221
	s_waitcnt lgkmcnt(5)
	v_add_f32_e32 v140, v140, v222
	s_waitcnt lgkmcnt(4)
	v_add_f32_e32 v141, v141, v223
	s_waitcnt lgkmcnt(3)
	v_add_f32_e32 v142, v142, v224
	s_waitcnt lgkmcnt(2)
	v_add_f32_e32 v143, v143, v225
	s_waitcnt lgkmcnt(1)
	v_add_f32_e32 v144, v144, v226
	s_waitcnt lgkmcnt(0)
	v_add_f32_e32 v145, v145, v227
	ds_bpermute_b32 v220, v173, v138
	ds_bpermute_b32 v221, v173, v139
	ds_bpermute_b32 v222, v173, v140
	ds_bpermute_b32 v223, v173, v141
	ds_bpermute_b32 v224, v173, v142
	ds_bpermute_b32 v225, v173, v143
	ds_bpermute_b32 v226, v173, v144
	ds_bpermute_b32 v227, v173, v145
	s_waitcnt lgkmcnt(7)
	v_add_f32_e32 v138, v138, v220
	s_waitcnt lgkmcnt(6)
	v_add_f32_e32 v139, v139, v221
	s_waitcnt lgkmcnt(5)
	v_add_f32_e32 v140, v140, v222
	s_waitcnt lgkmcnt(4)
	v_add_f32_e32 v141, v141, v223
	s_waitcnt lgkmcnt(3)
	v_add_f32_e32 v142, v142, v224
	s_waitcnt lgkmcnt(2)
	v_add_f32_e32 v143, v143, v225
	s_waitcnt lgkmcnt(1)
	v_add_f32_e32 v144, v144, v226
	s_waitcnt lgkmcnt(0)
	v_add_f32_e32 v145, v145, v227
	v_cmp_eq_u32_e32 vcc, 0, v174
	s_and_saveexec_b64 s[58:59], vcc
	global_store_dword v167, v130, s[10:11]
	global_store_dword v167, v131, s[10:11] offset:4
	global_store_dword v167, v132, s[10:11] offset:8
	global_store_dword v167, v133, s[10:11] offset:12
	global_store_dword v167, v134, s[10:11] offset:32
	global_store_dword v167, v135, s[10:11] offset:36
	global_store_dword v167, v136, s[10:11] offset:40
	global_store_dword v167, v137, s[10:11] offset:44
	global_store_dword v167, v138, s[10:11] offset:64
	global_store_dword v167, v139, s[10:11] offset:68
	global_store_dword v167, v140, s[10:11] offset:72
	global_store_dword v167, v141, s[10:11] offset:76
	global_store_dword v167, v142, s[10:11] offset:96
	global_store_dword v167, v143, s[10:11] offset:100
	global_store_dword v167, v144, s[10:11] offset:104
	global_store_dword v167, v145, s[10:11] offset:108
	s_mov_b64 exec, -1
	s_waitcnt vmcnt(46)
	v_fmac_f32_e32 v2, v34, v175
	v_fmac_f32_e32 v18, v50, v176
	global_store_dword v162, v2, s[48:49]
	global_store_dword v162, v18, s[48:49] offset:128
	s_waitcnt vmcnt(46)
	v_fmac_f32_e32 v3, v35, v175
	v_fmac_f32_e32 v19, v51, v176
	global_store_dword v163, v3, s[48:49]
	global_store_dword v163, v19, s[48:49] offset:128
	s_waitcnt vmcnt(46)
	v_fmac_f32_e32 v4, v36, v175
	v_fmac_f32_e32 v20, v52, v176
	global_store_dword v164, v4, s[48:49]
	global_store_dword v164, v20, s[48:49] offset:128
	s_waitcnt vmcnt(46)
	v_fmac_f32_e32 v5, v37, v175
	v_fmac_f32_e32 v21, v53, v176
	global_store_dword v165, v5, s[48:49]
	global_store_dword v165, v21, s[48:49] offset:128
	s_add_u32 s48, s48, 0x8000
	s_addc_u32 s49, s49, 0
	s_waitcnt vmcnt(46)
	v_fmac_f32_e32 v6, v38, v175
	v_fmac_f32_e32 v22, v54, v176
	global_store_dword v162, v6, s[48:49]
	global_store_dword v162, v22, s[48:49] offset:128
	s_waitcnt vmcnt(46)
	v_fmac_f32_e32 v7, v39, v175
	v_fmac_f32_e32 v23, v55, v176
	global_store_dword v163, v7, s[48:49]
	global_store_dword v163, v23, s[48:49] offset:128
	s_waitcnt vmcnt(46)
	v_fmac_f32_e32 v8, v40, v175
	v_fmac_f32_e32 v24, v56, v176
	global_store_dword v164, v8, s[48:49]
	global_store_dword v164, v24, s[48:49] offset:128
	s_waitcnt vmcnt(46)
	v_fmac_f32_e32 v9, v41, v175
	v_fmac_f32_e32 v25, v57, v176
	global_store_dword v165, v9, s[48:49]
	global_store_dword v165, v25, s[48:49] offset:128
	s_add_u32 s48, s48, 0x8000
	s_addc_u32 s49, s49, 0
	s_waitcnt vmcnt(46)
	v_fmac_f32_e32 v10, v42, v175
	v_fmac_f32_e32 v26, v58, v176
	global_store_dword v162, v10, s[48:49]
	global_store_dword v162, v26, s[48:49] offset:128
	s_waitcnt vmcnt(46)
	v_fmac_f32_e32 v11, v43, v175
	v_fmac_f32_e32 v27, v59, v176
	global_store_dword v163, v11, s[48:49]
	global_store_dword v163, v27, s[48:49] offset:128
	s_waitcnt vmcnt(46)
	v_fmac_f32_e32 v12, v44, v175
	v_fmac_f32_e32 v28, v60, v176
	global_store_dword v164, v12, s[48:49]
	global_store_dword v164, v28, s[48:49] offset:128
	s_waitcnt vmcnt(46)
	v_fmac_f32_e32 v13, v45, v175
	v_fmac_f32_e32 v29, v61, v176
	global_store_dword v165, v13, s[48:49]
	global_store_dword v165, v29, s[48:49] offset:128
	s_add_u32 s48, s48, 0x8000
	s_addc_u32 s49, s49, 0
	s_waitcnt vmcnt(46)
	v_fmac_f32_e32 v14, v46, v175
	v_fmac_f32_e32 v30, v62, v176
	global_store_dword v162, v14, s[48:49]
	global_store_dword v162, v30, s[48:49] offset:128
	s_waitcnt vmcnt(46)
	v_fmac_f32_e32 v15, v47, v175
	v_fmac_f32_e32 v31, v63, v176
	global_store_dword v163, v15, s[48:49]
	global_store_dword v163, v31, s[48:49] offset:128
	s_waitcnt vmcnt(46)
	v_fmac_f32_e32 v16, v48, v175
	v_fmac_f32_e32 v32, v64, v176
	global_store_dword v164, v16, s[48:49]
	global_store_dword v164, v32, s[48:49] offset:128
	s_waitcnt vmcnt(46)
	v_fmac_f32_e32 v17, v49, v175
	v_fmac_f32_e32 v33, v65, v176
	global_store_dword v165, v17, s[48:49]
	global_store_dword v165, v33, s[48:49] offset:128
	s_sub_u32 s48, s48, 0x18000
	s_subb_u32 s49, s49, 0
	s_sub_u32 s48, s48, 0x1fe00
	s_subb_u32 s49, s49, 0
	s_add_u32 s60, s60, 0x200
	s_addc_u32 s61, s61, 0
	global_load_dword v175, v166, s[60:61]
	global_load_dword v176, v166, s[60:61] offset:128
	global_load_dword v34, v162, s[48:49]
	global_load_dword v50, v162, s[48:49] offset:128
	global_load_dword v35, v163, s[48:49]
	global_load_dword v51, v163, s[48:49] offset:128
	global_load_dword v36, v164, s[48:49]
	global_load_dword v52, v164, s[48:49] offset:128
	global_load_dword v37, v165, s[48:49]
	global_load_dword v53, v165, s[48:49] offset:128
	s_add_u32 s48, s48, 0x8000
	s_addc_u32 s49, s49, 0
	global_load_dword v38, v162, s[48:49]
	global_load_dword v54, v162, s[48:49] offset:128
	global_load_dword v39, v163, s[48:49]
	global_load_dword v55, v163, s[48:49] offset:128
	global_load_dword v40, v164, s[48:49]
	global_load_dword v56, v164, s[48:49] offset:128
	global_load_dword v41, v165, s[48:49]
	global_load_dword v57, v165, s[48:49] offset:128
	s_add_u32 s48, s48, 0x8000
	s_addc_u32 s49, s49, 0
	global_load_dword v42, v162, s[48:49]
	global_load_dword v58, v162, s[48:49] offset:128
	global_load_dword v43, v163, s[48:49]
	global_load_dword v59, v163, s[48:49] offset:128
	global_load_dword v44, v164, s[48:49]
	global_load_dword v60, v164, s[48:49] offset:128
	global_load_dword v45, v165, s[48:49]
	global_load_dword v61, v165, s[48:49] offset:128
	s_add_u32 s48, s48, 0x8000
	s_addc_u32 s49, s49, 0
	global_load_dword v46, v162, s[48:49]
	global_load_dword v62, v162, s[48:49] offset:128
	global_load_dword v47, v163, s[48:49]
	global_load_dword v63, v163, s[48:49] offset:128
	global_load_dword v48, v164, s[48:49]
	global_load_dword v64, v164, s[48:49] offset:128
	global_load_dword v49, v165, s[48:49]
	global_load_dword v65, v165, s[48:49] offset:128
	s_sub_u32 s48, s48, 0x18000
	s_subb_u32 s49, s49, 0
	v_mul_f32_e32 v2, v2, v2
	v_fmac_f32_e32 v2, v18, v18
	v_mul_f32_e32 v3, v3, v3
	v_fmac_f32_e32 v3, v19, v19
	v_mul_f32_e32 v4, v4, v4
	v_fmac_f32_e32 v4, v20, v20
	v_mul_f32_e32 v5, v5, v5
	v_fmac_f32_e32 v5, v21, v21
	v_mul_f32_e32 v6, v6, v6
	v_fmac_f32_e32 v6, v22, v22
	v_mul_f32_e32 v7, v7, v7
	v_fmac_f32_e32 v7, v23, v23
	v_mul_f32_e32 v8, v8, v8
	v_fmac_f32_e32 v8, v24, v24
	v_mul_f32_e32 v9, v9, v9
	v_fmac_f32_e32 v9, v25, v25
	v_mul_f32_e32 v10, v10, v10
	v_fmac_f32_e32 v10, v26, v26
	v_mul_f32_e32 v11, v11, v11
	v_fmac_f32_e32 v11, v27, v27
	v_mul_f32_e32 v12, v12, v12
	v_fmac_f32_e32 v12, v28, v28
	v_mul_f32_e32 v13, v13, v13
	v_fmac_f32_e32 v13, v29, v29
	v_mul_f32_e32 v14, v14, v14
	v_fmac_f32_e32 v14, v30, v30
	v_mul_f32_e32 v15, v15, v15
	v_fmac_f32_e32 v15, v31, v31
	v_mul_f32_e32 v16, v16, v16
	v_fmac_f32_e32 v16, v32, v32
	v_mul_f32_e32 v17, v17, v17
	v_fmac_f32_e32 v17, v33, v33
	s_waitcnt lgkmcnt(0)
	ds_bpermute_b32 v18, v168, v2
	ds_bpermute_b32 v19, v168, v3
	ds_bpermute_b32 v20, v168, v4
	ds_bpermute_b32 v21, v168, v5
	ds_bpermute_b32 v22, v168, v6
	ds_bpermute_b32 v23, v168, v7
	ds_bpermute_b32 v24, v168, v8
	ds_bpermute_b32 v25, v168, v9
	s_waitcnt lgkmcnt(7)
	v_add_f32_e32 v2, v2, v18
	s_waitcnt lgkmcnt(6)
	v_add_f32_e32 v3, v3, v19
	s_waitcnt lgkmcnt(5)
	v_add_f32_e32 v4, v4, v20
	s_waitcnt lgkmcnt(4)
	v_add_f32_e32 v5, v5, v21
	s_waitcnt lgkmcnt(3)
	v_add_f32_e32 v6, v6, v22
	s_waitcnt lgkmcnt(2)
	v_add_f32_e32 v7, v7, v23
	s_waitcnt lgkmcnt(1)
	v_add_f32_e32 v8, v8, v24
	s_waitcnt lgkmcnt(0)
	v_add_f32_e32 v9, v9, v25
	ds_bpermute_b32 v18, v169, v2
	ds_bpermute_b32 v19, v169, v3
	ds_bpermute_b32 v20, v169, v4
	ds_bpermute_b32 v21, v169, v5
	ds_bpermute_b32 v22, v169, v6
	ds_bpermute_b32 v23, v169, v7
	ds_bpermute_b32 v24, v169, v8
	ds_bpermute_b32 v25, v169, v9
	s_waitcnt lgkmcnt(7)
	v_add_f32_e32 v2, v2, v18
	s_waitcnt lgkmcnt(6)
	v_add_f32_e32 v3, v3, v19
	s_waitcnt lgkmcnt(5)
	v_add_f32_e32 v4, v4, v20
	s_waitcnt lgkmcnt(4)
	v_add_f32_e32 v5, v5, v21
	s_waitcnt lgkmcnt(3)
	v_add_f32_e32 v6, v6, v22
	s_waitcnt lgkmcnt(2)
	v_add_f32_e32 v7, v7, v23
	s_waitcnt lgkmcnt(1)
	v_add_f32_e32 v8, v8, v24
	s_waitcnt lgkmcnt(0)
	v_add_f32_e32 v9, v9, v25
	ds_bpermute_b32 v18, v171, v2
	ds_bpermute_b32 v19, v171, v3
	ds_bpermute_b32 v20, v171, v4
	ds_bpermute_b32 v21, v171, v5
	ds_bpermute_b32 v22, v171, v6
	ds_bpermute_b32 v23, v171, v7
	ds_bpermute_b32 v24, v171, v8
	ds_bpermute_b32 v25, v171, v9
	s_waitcnt lgkmcnt(7)
	v_add_f32_e32 v2, v2, v18
	s_waitcnt lgkmcnt(6)
	v_add_f32_e32 v3, v3, v19
	s_waitcnt lgkmcnt(5)
	v_add_f32_e32 v4, v4, v20
	s_waitcnt lgkmcnt(4)
	v_add_f32_e32 v5, v5, v21
	s_waitcnt lgkmcnt(3)
	v_add_f32_e32 v6, v6, v22
	s_waitcnt lgkmcnt(2)
	v_add_f32_e32 v7, v7, v23
	s_waitcnt lgkmcnt(1)
	v_add_f32_e32 v8, v8, v24
	s_waitcnt lgkmcnt(0)
	v_add_f32_e32 v9, v9, v25
	ds_bpermute_b32 v18, v172, v2
	ds_bpermute_b32 v19, v172, v3
	ds_bpermute_b32 v20, v172, v4
	ds_bpermute_b32 v21, v172, v5
	ds_bpermute_b32 v22, v172, v6
	ds_bpermute_b32 v23, v172, v7
	ds_bpermute_b32 v24, v172, v8
	ds_bpermute_b32 v25, v172, v9
	s_waitcnt lgkmcnt(7)
	v_add_f32_e32 v2, v2, v18
	s_waitcnt lgkmcnt(6)
	v_add_f32_e32 v3, v3, v19
	s_waitcnt lgkmcnt(5)
	v_add_f32_e32 v4, v4, v20
	s_waitcnt lgkmcnt(4)
	v_add_f32_e32 v5, v5, v21
	s_waitcnt lgkmcnt(3)
	v_add_f32_e32 v6, v6, v22
	s_waitcnt lgkmcnt(2)
	v_add_f32_e32 v7, v7, v23
	s_waitcnt lgkmcnt(1)
	v_add_f32_e32 v8, v8, v24
	s_waitcnt lgkmcnt(0)
	v_add_f32_e32 v9, v9, v25
	ds_bpermute_b32 v18, v173, v2
	ds_bpermute_b32 v19, v173, v3
	ds_bpermute_b32 v20, v173, v4
	ds_bpermute_b32 v21, v173, v5
	ds_bpermute_b32 v22, v173, v6
	ds_bpermute_b32 v23, v173, v7
	ds_bpermute_b32 v24, v173, v8
	ds_bpermute_b32 v25, v173, v9
	s_waitcnt lgkmcnt(7)
	v_add_f32_e32 v2, v2, v18
	s_waitcnt lgkmcnt(6)
	v_add_f32_e32 v3, v3, v19
	s_waitcnt lgkmcnt(5)
	v_add_f32_e32 v4, v4, v20
	s_waitcnt lgkmcnt(4)
	v_add_f32_e32 v5, v5, v21
	s_waitcnt lgkmcnt(3)
	v_add_f32_e32 v6, v6, v22
	s_waitcnt lgkmcnt(2)
	v_add_f32_e32 v7, v7, v23
	s_waitcnt lgkmcnt(1)
	v_add_f32_e32 v8, v8, v24
	s_waitcnt lgkmcnt(0)
	v_add_f32_e32 v9, v9, v25
	ds_bpermute_b32 v26, v168, v10
	ds_bpermute_b32 v27, v168, v11
	ds_bpermute_b32 v28, v168, v12
	ds_bpermute_b32 v29, v168, v13
	ds_bpermute_b32 v30, v168, v14
	ds_bpermute_b32 v31, v168, v15
	ds_bpermute_b32 v32, v168, v16
	ds_bpermute_b32 v33, v168, v17
	s_waitcnt lgkmcnt(7)
	v_add_f32_e32 v10, v10, v26
	s_waitcnt lgkmcnt(6)
	v_add_f32_e32 v11, v11, v27
	s_waitcnt lgkmcnt(5)
	v_add_f32_e32 v12, v12, v28
	s_waitcnt lgkmcnt(4)
	v_add_f32_e32 v13, v13, v29
	s_waitcnt lgkmcnt(3)
	v_add_f32_e32 v14, v14, v30
	s_waitcnt lgkmcnt(2)
	v_add_f32_e32 v15, v15, v31
	s_waitcnt lgkmcnt(1)
	v_add_f32_e32 v16, v16, v32
	s_waitcnt lgkmcnt(0)
	v_add_f32_e32 v17, v17, v33
	ds_bpermute_b32 v26, v169, v10
	ds_bpermute_b32 v27, v169, v11
	ds_bpermute_b32 v28, v169, v12
	ds_bpermute_b32 v29, v169, v13
	ds_bpermute_b32 v30, v169, v14
	ds_bpermute_b32 v31, v169, v15
	ds_bpermute_b32 v32, v169, v16
	ds_bpermute_b32 v33, v169, v17
	s_waitcnt lgkmcnt(7)
	v_add_f32_e32 v10, v10, v26
	s_waitcnt lgkmcnt(6)
	v_add_f32_e32 v11, v11, v27
	s_waitcnt lgkmcnt(5)
	v_add_f32_e32 v12, v12, v28
	s_waitcnt lgkmcnt(4)
	v_add_f32_e32 v13, v13, v29
	s_waitcnt lgkmcnt(3)
	v_add_f32_e32 v14, v14, v30
	s_waitcnt lgkmcnt(2)
	v_add_f32_e32 v15, v15, v31
	s_waitcnt lgkmcnt(1)
	v_add_f32_e32 v16, v16, v32
	s_waitcnt lgkmcnt(0)
	v_add_f32_e32 v17, v17, v33
	ds_bpermute_b32 v26, v171, v10
	ds_bpermute_b32 v27, v171, v11
	ds_bpermute_b32 v28, v171, v12
	ds_bpermute_b32 v29, v171, v13
	ds_bpermute_b32 v30, v171, v14
	ds_bpermute_b32 v31, v171, v15
	ds_bpermute_b32 v32, v171, v16
	ds_bpermute_b32 v33, v171, v17
	s_waitcnt lgkmcnt(7)
	v_add_f32_e32 v10, v10, v26
	s_waitcnt lgkmcnt(6)
	v_add_f32_e32 v11, v11, v27
	s_waitcnt lgkmcnt(5)
	v_add_f32_e32 v12, v12, v28
	s_waitcnt lgkmcnt(4)
	v_add_f32_e32 v13, v13, v29
	s_waitcnt lgkmcnt(3)
	v_add_f32_e32 v14, v14, v30
	s_waitcnt lgkmcnt(2)
	v_add_f32_e32 v15, v15, v31
	s_waitcnt lgkmcnt(1)
	v_add_f32_e32 v16, v16, v32
	s_waitcnt lgkmcnt(0)
	v_add_f32_e32 v17, v17, v33
	ds_bpermute_b32 v26, v172, v10
	ds_bpermute_b32 v27, v172, v11
	ds_bpermute_b32 v28, v172, v12
	ds_bpermute_b32 v29, v172, v13
	ds_bpermute_b32 v30, v172, v14
	ds_bpermute_b32 v31, v172, v15
	ds_bpermute_b32 v32, v172, v16
	ds_bpermute_b32 v33, v172, v17
	s_waitcnt lgkmcnt(7)
	v_add_f32_e32 v10, v10, v26
	s_waitcnt lgkmcnt(6)
	v_add_f32_e32 v11, v11, v27
	s_waitcnt lgkmcnt(5)
	v_add_f32_e32 v12, v12, v28
	s_waitcnt lgkmcnt(4)
	v_add_f32_e32 v13, v13, v29
	s_waitcnt lgkmcnt(3)
	v_add_f32_e32 v14, v14, v30
	s_waitcnt lgkmcnt(2)
	v_add_f32_e32 v15, v15, v31
	s_waitcnt lgkmcnt(1)
	v_add_f32_e32 v16, v16, v32
	s_waitcnt lgkmcnt(0)
	v_add_f32_e32 v17, v17, v33
	ds_bpermute_b32 v26, v173, v10
	ds_bpermute_b32 v27, v173, v11
	ds_bpermute_b32 v28, v173, v12
	ds_bpermute_b32 v29, v173, v13
	ds_bpermute_b32 v30, v173, v14
	ds_bpermute_b32 v31, v173, v15
	ds_bpermute_b32 v32, v173, v16
	ds_bpermute_b32 v33, v173, v17
	s_waitcnt lgkmcnt(7)
	v_add_f32_e32 v10, v10, v26
	s_waitcnt lgkmcnt(6)
	v_add_f32_e32 v11, v11, v27
	s_waitcnt lgkmcnt(5)
	v_add_f32_e32 v12, v12, v28
	s_waitcnt lgkmcnt(4)
	v_add_f32_e32 v13, v13, v29
	s_waitcnt lgkmcnt(3)
	v_add_f32_e32 v14, v14, v30
	s_waitcnt lgkmcnt(2)
	v_add_f32_e32 v15, v15, v31
	s_waitcnt lgkmcnt(1)
	v_add_f32_e32 v16, v16, v32
	s_waitcnt lgkmcnt(0)
	v_add_f32_e32 v17, v17, v33
	v_cmp_eq_u32_e32 vcc, 0, v174
	s_and_saveexec_b64 s[58:59], vcc
	global_store_dword v167, v2, s[10:11] offset:128
	global_store_dword v167, v3, s[10:11] offset:132
	global_store_dword v167, v4, s[10:11] offset:136
	global_store_dword v167, v5, s[10:11] offset:140
	global_store_dword v167, v6, s[10:11] offset:160
	global_store_dword v167, v7, s[10:11] offset:164
	global_store_dword v167, v8, s[10:11] offset:168
	global_store_dword v167, v9, s[10:11] offset:172
	global_store_dword v167, v10, s[10:11] offset:192
	global_store_dword v167, v11, s[10:11] offset:196
	global_store_dword v167, v12, s[10:11] offset:200
	global_store_dword v167, v13, s[10:11] offset:204
	global_store_dword v167, v14, s[10:11] offset:224
	global_store_dword v167, v15, s[10:11] offset:228
	global_store_dword v167, v16, s[10:11] offset:232
	global_store_dword v167, v17, s[10:11] offset:236
	s_mov_b64 exec, -1
	s_add_u32 s10, s10, 0x18000
	s_addc_u32 s11, s11, 0
	s_waitcnt vmcnt(46)
	s_waitcnt vmcnt(46)
	v_fmac_f32_e32 v34, v66, v175
	v_fmac_f32_e32 v50, v82, v176
	global_store_dword v162, v34, s[48:49]
	global_store_dword v162, v50, s[48:49] offset:128
	s_waitcnt vmcnt(46)
	v_fmac_f32_e32 v35, v67, v175
	v_fmac_f32_e32 v51, v83, v176
	global_store_dword v163, v35, s[48:49]
	global_store_dword v163, v51, s[48:49] offset:128
	s_waitcnt vmcnt(46)
	v_fmac_f32_e32 v36, v68, v175
	v_fmac_f32_e32 v52, v84, v176
	global_store_dword v164, v36, s[48:49]
	global_store_dword v164, v52, s[48:49] offset:128
	s_waitcnt vmcnt(46)
	v_fmac_f32_e32 v37, v69, v175
	v_fmac_f32_e32 v53, v85, v176
	global_store_dword v165, v37, s[48:49]
	global_store_dword v165, v53, s[48:49] offset:128
	s_add_u32 s48, s48, 0x8000
	s_addc_u32 s49, s49, 0
	s_waitcnt vmcnt(46)
	v_fmac_f32_e32 v38, v70, v175
	v_fmac_f32_e32 v54, v86, v176
	global_store_dword v162, v38, s[48:49]
	global_store_dword v162, v54, s[48:49] offset:128
	s_waitcnt vmcnt(46)
	v_fmac_f32_e32 v39, v71, v175
	v_fmac_f32_e32 v55, v87, v176
	global_store_dword v163, v39, s[48:49]
	global_store_dword v163, v55, s[48:49] offset:128
	s_waitcnt vmcnt(46)
	v_fmac_f32_e32 v40, v72, v175
	v_fmac_f32_e32 v56, v88, v176
	global_store_dword v164, v40, s[48:49]
	global_store_dword v164, v56, s[48:49] offset:128
	s_waitcnt vmcnt(46)
	v_fmac_f32_e32 v41, v73, v175
	v_fmac_f32_e32 v57, v89, v176
	global_store_dword v165, v41, s[48:49]
	global_store_dword v165, v57, s[48:49] offset:128
	s_add_u32 s48, s48, 0x8000
	s_addc_u32 s49, s49, 0
	s_waitcnt vmcnt(46)
	v_fmac_f32_e32 v42, v74, v175
	v_fmac_f32_e32 v58, v90, v176
	global_store_dword v162, v42, s[48:49]
	global_store_dword v162, v58, s[48:49] offset:128
	s_waitcnt vmcnt(46)
	v_fmac_f32_e32 v43, v75, v175
	v_fmac_f32_e32 v59, v91, v176
	global_store_dword v163, v43, s[48:49]
	global_store_dword v163, v59, s[48:49] offset:128
	s_waitcnt vmcnt(46)
	v_fmac_f32_e32 v44, v76, v175
	v_fmac_f32_e32 v60, v92, v176
	global_store_dword v164, v44, s[48:49]
	global_store_dword v164, v60, s[48:49] offset:128
	s_waitcnt vmcnt(46)
	v_fmac_f32_e32 v45, v77, v175
	v_fmac_f32_e32 v61, v93, v176
	global_store_dword v165, v45, s[48:49]
	global_store_dword v165, v61, s[48:49] offset:128
	s_add_u32 s48, s48, 0x8000
	s_addc_u32 s49, s49, 0
	s_waitcnt vmcnt(46)
	v_fmac_f32_e32 v46, v78, v175
	v_fmac_f32_e32 v62, v94, v176
	global_store_dword v162, v46, s[48:49]
	global_store_dword v162, v62, s[48:49] offset:128
	s_waitcnt vmcnt(46)
	v_fmac_f32_e32 v47, v79, v175
	v_fmac_f32_e32 v63, v95, v176
	global_store_dword v163, v47, s[48:49]
	global_store_dword v163, v63, s[48:49] offset:128
	s_waitcnt vmcnt(46)
	v_fmac_f32_e32 v48, v80, v175
	v_fmac_f32_e32 v64, v96, v176
	global_store_dword v164, v48, s[48:49]
	global_store_dword v164, v64, s[48:49] offset:128
	s_waitcnt vmcnt(46)
	v_fmac_f32_e32 v49, v81, v175
	v_fmac_f32_e32 v65, v97, v176
	global_store_dword v165, v49, s[48:49]
	global_store_dword v165, v65, s[48:49] offset:128
	s_sub_u32 s48, s48, 0x18000
	s_subb_u32 s49, s49, 0
	s_add_u32 s48, s48, 0x20000
	s_addc_u32 s49, s49, 0
	global_load_dword v66, v162, s[48:49]
	global_load_dword v82, v162, s[48:49] offset:128
	global_load_dword v67, v163, s[48:49]
	global_load_dword v83, v163, s[48:49] offset:128
	global_load_dword v68, v164, s[48:49]
	global_load_dword v84, v164, s[48:49] offset:128
	global_load_dword v69, v165, s[48:49]
	global_load_dword v85, v165, s[48:49] offset:128
	s_add_u32 s48, s48, 0x8000
	s_addc_u32 s49, s49, 0
	global_load_dword v70, v162, s[48:49]
	global_load_dword v86, v162, s[48:49] offset:128
	global_load_dword v71, v163, s[48:49]
	global_load_dword v87, v163, s[48:49] offset:128
	global_load_dword v72, v164, s[48:49]
	global_load_dword v88, v164, s[48:49] offset:128
	global_load_dword v73, v165, s[48:49]
	global_load_dword v89, v165, s[48:49] offset:128
	s_add_u32 s48, s48, 0x8000
	s_addc_u32 s49, s49, 0
	global_load_dword v74, v162, s[48:49]
	global_load_dword v90, v162, s[48:49] offset:128
	global_load_dword v75, v163, s[48:49]
	global_load_dword v91, v163, s[48:49] offset:128
	global_load_dword v76, v164, s[48:49]
	global_load_dword v92, v164, s[48:49] offset:128
	global_load_dword v77, v165, s[48:49]
	global_load_dword v93, v165, s[48:49] offset:128
	s_add_u32 s48, s48, 0x8000
	s_addc_u32 s49, s49, 0
	global_load_dword v78, v162, s[48:49]
	global_load_dword v94, v162, s[48:49] offset:128
	global_load_dword v79, v163, s[48:49]
	global_load_dword v95, v163, s[48:49] offset:128
	global_load_dword v80, v164, s[48:49]
	global_load_dword v96, v164, s[48:49] offset:128
	global_load_dword v81, v165, s[48:49]
	global_load_dword v97, v165, s[48:49] offset:128
	s_sub_u32 s48, s48, 0x18000
	s_subb_u32 s49, s49, 0
	v_mul_f32_e32 v34, v34, v34
	v_fmac_f32_e32 v34, v50, v50
	v_mul_f32_e32 v35, v35, v35
	v_fmac_f32_e32 v35, v51, v51
	v_mul_f32_e32 v36, v36, v36
	v_fmac_f32_e32 v36, v52, v52
	v_mul_f32_e32 v37, v37, v37
	v_fmac_f32_e32 v37, v53, v53
	v_mul_f32_e32 v38, v38, v38
	v_fmac_f32_e32 v38, v54, v54
	v_mul_f32_e32 v39, v39, v39
	v_fmac_f32_e32 v39, v55, v55
	v_mul_f32_e32 v40, v40, v40
	v_fmac_f32_e32 v40, v56, v56
	v_mul_f32_e32 v41, v41, v41
	v_fmac_f32_e32 v41, v57, v57
	v_mul_f32_e32 v42, v42, v42
	v_fmac_f32_e32 v42, v58, v58
	v_mul_f32_e32 v43, v43, v43
	v_fmac_f32_e32 v43, v59, v59
	v_mul_f32_e32 v44, v44, v44
	v_fmac_f32_e32 v44, v60, v60
	v_mul_f32_e32 v45, v45, v45
	v_fmac_f32_e32 v45, v61, v61
	v_mul_f32_e32 v46, v46, v46
	v_fmac_f32_e32 v46, v62, v62
	v_mul_f32_e32 v47, v47, v47
	v_fmac_f32_e32 v47, v63, v63
	v_mul_f32_e32 v48, v48, v48
	v_fmac_f32_e32 v48, v64, v64
	v_mul_f32_e32 v49, v49, v49
	v_fmac_f32_e32 v49, v65, v65
	s_waitcnt lgkmcnt(0)
	ds_bpermute_b32 v50, v168, v34
	ds_bpermute_b32 v51, v168, v35
	ds_bpermute_b32 v52, v168, v36
	ds_bpermute_b32 v53, v168, v37
	ds_bpermute_b32 v54, v168, v38
	ds_bpermute_b32 v55, v168, v39
	ds_bpermute_b32 v56, v168, v40
	ds_bpermute_b32 v57, v168, v41
	s_waitcnt lgkmcnt(7)
	v_add_f32_e32 v34, v34, v50
	s_waitcnt lgkmcnt(6)
	v_add_f32_e32 v35, v35, v51
	s_waitcnt lgkmcnt(5)
	v_add_f32_e32 v36, v36, v52
	s_waitcnt lgkmcnt(4)
	v_add_f32_e32 v37, v37, v53
	s_waitcnt lgkmcnt(3)
	v_add_f32_e32 v38, v38, v54
	s_waitcnt lgkmcnt(2)
	v_add_f32_e32 v39, v39, v55
	s_waitcnt lgkmcnt(1)
	v_add_f32_e32 v40, v40, v56
	s_waitcnt lgkmcnt(0)
	v_add_f32_e32 v41, v41, v57
	ds_bpermute_b32 v50, v169, v34
	ds_bpermute_b32 v51, v169, v35
	ds_bpermute_b32 v52, v169, v36
	ds_bpermute_b32 v53, v169, v37
	ds_bpermute_b32 v54, v169, v38
	ds_bpermute_b32 v55, v169, v39
	ds_bpermute_b32 v56, v169, v40
	ds_bpermute_b32 v57, v169, v41
	s_waitcnt lgkmcnt(7)
	v_add_f32_e32 v34, v34, v50
	s_waitcnt lgkmcnt(6)
	v_add_f32_e32 v35, v35, v51
	s_waitcnt lgkmcnt(5)
	v_add_f32_e32 v36, v36, v52
	s_waitcnt lgkmcnt(4)
	v_add_f32_e32 v37, v37, v53
	s_waitcnt lgkmcnt(3)
	v_add_f32_e32 v38, v38, v54
	s_waitcnt lgkmcnt(2)
	v_add_f32_e32 v39, v39, v55
	s_waitcnt lgkmcnt(1)
	v_add_f32_e32 v40, v40, v56
	s_waitcnt lgkmcnt(0)
	v_add_f32_e32 v41, v41, v57
	ds_bpermute_b32 v50, v171, v34
	ds_bpermute_b32 v51, v171, v35
	ds_bpermute_b32 v52, v171, v36
	ds_bpermute_b32 v53, v171, v37
	ds_bpermute_b32 v54, v171, v38
	ds_bpermute_b32 v55, v171, v39
	ds_bpermute_b32 v56, v171, v40
	ds_bpermute_b32 v57, v171, v41
	s_waitcnt lgkmcnt(7)
	v_add_f32_e32 v34, v34, v50
	s_waitcnt lgkmcnt(6)
	v_add_f32_e32 v35, v35, v51
	s_waitcnt lgkmcnt(5)
	v_add_f32_e32 v36, v36, v52
	s_waitcnt lgkmcnt(4)
	v_add_f32_e32 v37, v37, v53
	s_waitcnt lgkmcnt(3)
	v_add_f32_e32 v38, v38, v54
	s_waitcnt lgkmcnt(2)
	v_add_f32_e32 v39, v39, v55
	s_waitcnt lgkmcnt(1)
	v_add_f32_e32 v40, v40, v56
	s_waitcnt lgkmcnt(0)
	v_add_f32_e32 v41, v41, v57
	ds_bpermute_b32 v50, v172, v34
	ds_bpermute_b32 v51, v172, v35
	ds_bpermute_b32 v52, v172, v36
	ds_bpermute_b32 v53, v172, v37
	ds_bpermute_b32 v54, v172, v38
	ds_bpermute_b32 v55, v172, v39
	ds_bpermute_b32 v56, v172, v40
	ds_bpermute_b32 v57, v172, v41
	s_waitcnt lgkmcnt(7)
	v_add_f32_e32 v34, v34, v50
	s_waitcnt lgkmcnt(6)
	v_add_f32_e32 v35, v35, v51
	s_waitcnt lgkmcnt(5)
	v_add_f32_e32 v36, v36, v52
	s_waitcnt lgkmcnt(4)
	v_add_f32_e32 v37, v37, v53
	s_waitcnt lgkmcnt(3)
	v_add_f32_e32 v38, v38, v54
	s_waitcnt lgkmcnt(2)
	v_add_f32_e32 v39, v39, v55
	s_waitcnt lgkmcnt(1)
	v_add_f32_e32 v40, v40, v56
	s_waitcnt lgkmcnt(0)
	v_add_f32_e32 v41, v41, v57
	ds_bpermute_b32 v50, v173, v34
	ds_bpermute_b32 v51, v173, v35
	ds_bpermute_b32 v52, v173, v36
	ds_bpermute_b32 v53, v173, v37
	ds_bpermute_b32 v54, v173, v38
	ds_bpermute_b32 v55, v173, v39
	ds_bpermute_b32 v56, v173, v40
	ds_bpermute_b32 v57, v173, v41
	s_waitcnt lgkmcnt(7)
	v_add_f32_e32 v34, v34, v50
	s_waitcnt lgkmcnt(6)
	v_add_f32_e32 v35, v35, v51
	s_waitcnt lgkmcnt(5)
	v_add_f32_e32 v36, v36, v52
	s_waitcnt lgkmcnt(4)
	v_add_f32_e32 v37, v37, v53
	s_waitcnt lgkmcnt(3)
	v_add_f32_e32 v38, v38, v54
	s_waitcnt lgkmcnt(2)
	v_add_f32_e32 v39, v39, v55
	s_waitcnt lgkmcnt(1)
	v_add_f32_e32 v40, v40, v56
	s_waitcnt lgkmcnt(0)
	v_add_f32_e32 v41, v41, v57
	ds_bpermute_b32 v58, v168, v42
	ds_bpermute_b32 v59, v168, v43
	ds_bpermute_b32 v60, v168, v44
	ds_bpermute_b32 v61, v168, v45
	ds_bpermute_b32 v62, v168, v46
	ds_bpermute_b32 v63, v168, v47
	ds_bpermute_b32 v64, v168, v48
	ds_bpermute_b32 v65, v168, v49
	s_waitcnt lgkmcnt(7)
	v_add_f32_e32 v42, v42, v58
	s_waitcnt lgkmcnt(6)
	v_add_f32_e32 v43, v43, v59
	s_waitcnt lgkmcnt(5)
	v_add_f32_e32 v44, v44, v60
	s_waitcnt lgkmcnt(4)
	v_add_f32_e32 v45, v45, v61
	s_waitcnt lgkmcnt(3)
	v_add_f32_e32 v46, v46, v62
	s_waitcnt lgkmcnt(2)
	v_add_f32_e32 v47, v47, v63
	s_waitcnt lgkmcnt(1)
	v_add_f32_e32 v48, v48, v64
	s_waitcnt lgkmcnt(0)
	v_add_f32_e32 v49, v49, v65
	ds_bpermute_b32 v58, v169, v42
	ds_bpermute_b32 v59, v169, v43
	ds_bpermute_b32 v60, v169, v44
	ds_bpermute_b32 v61, v169, v45
	ds_bpermute_b32 v62, v169, v46
	ds_bpermute_b32 v63, v169, v47
	ds_bpermute_b32 v64, v169, v48
	ds_bpermute_b32 v65, v169, v49
	s_waitcnt lgkmcnt(7)
	v_add_f32_e32 v42, v42, v58
	s_waitcnt lgkmcnt(6)
	v_add_f32_e32 v43, v43, v59
	s_waitcnt lgkmcnt(5)
	v_add_f32_e32 v44, v44, v60
	s_waitcnt lgkmcnt(4)
	v_add_f32_e32 v45, v45, v61
	s_waitcnt lgkmcnt(3)
	v_add_f32_e32 v46, v46, v62
	s_waitcnt lgkmcnt(2)
	v_add_f32_e32 v47, v47, v63
	s_waitcnt lgkmcnt(1)
	v_add_f32_e32 v48, v48, v64
	s_waitcnt lgkmcnt(0)
	v_add_f32_e32 v49, v49, v65
	ds_bpermute_b32 v58, v171, v42
	ds_bpermute_b32 v59, v171, v43
	ds_bpermute_b32 v60, v171, v44
	ds_bpermute_b32 v61, v171, v45
	ds_bpermute_b32 v62, v171, v46
	ds_bpermute_b32 v63, v171, v47
	ds_bpermute_b32 v64, v171, v48
	ds_bpermute_b32 v65, v171, v49
	s_waitcnt lgkmcnt(7)
	v_add_f32_e32 v42, v42, v58
	s_waitcnt lgkmcnt(6)
	v_add_f32_e32 v43, v43, v59
	s_waitcnt lgkmcnt(5)
	v_add_f32_e32 v44, v44, v60
	s_waitcnt lgkmcnt(4)
	v_add_f32_e32 v45, v45, v61
	s_waitcnt lgkmcnt(3)
	v_add_f32_e32 v46, v46, v62
	s_waitcnt lgkmcnt(2)
	v_add_f32_e32 v47, v47, v63
	s_waitcnt lgkmcnt(1)
	v_add_f32_e32 v48, v48, v64
	s_waitcnt lgkmcnt(0)
	v_add_f32_e32 v49, v49, v65
	ds_bpermute_b32 v58, v172, v42
	ds_bpermute_b32 v59, v172, v43
	ds_bpermute_b32 v60, v172, v44
	ds_bpermute_b32 v61, v172, v45
	ds_bpermute_b32 v62, v172, v46
	ds_bpermute_b32 v63, v172, v47
	ds_bpermute_b32 v64, v172, v48
	ds_bpermute_b32 v65, v172, v49
	s_waitcnt lgkmcnt(7)
	v_add_f32_e32 v42, v42, v58
	s_waitcnt lgkmcnt(6)
	v_add_f32_e32 v43, v43, v59
	s_waitcnt lgkmcnt(5)
	v_add_f32_e32 v44, v44, v60
	s_waitcnt lgkmcnt(4)
	v_add_f32_e32 v45, v45, v61
	s_waitcnt lgkmcnt(3)
	v_add_f32_e32 v46, v46, v62
	s_waitcnt lgkmcnt(2)
	v_add_f32_e32 v47, v47, v63
	s_waitcnt lgkmcnt(1)
	v_add_f32_e32 v48, v48, v64
	s_waitcnt lgkmcnt(0)
	v_add_f32_e32 v49, v49, v65
	ds_bpermute_b32 v58, v173, v42
	ds_bpermute_b32 v59, v173, v43
	ds_bpermute_b32 v60, v173, v44
	ds_bpermute_b32 v61, v173, v45
	ds_bpermute_b32 v62, v173, v46
	ds_bpermute_b32 v63, v173, v47
	ds_bpermute_b32 v64, v173, v48
	ds_bpermute_b32 v65, v173, v49
	s_waitcnt lgkmcnt(7)
	v_add_f32_e32 v42, v42, v58
	s_waitcnt lgkmcnt(6)
	v_add_f32_e32 v43, v43, v59
	s_waitcnt lgkmcnt(5)
	v_add_f32_e32 v44, v44, v60
	s_waitcnt lgkmcnt(4)
	v_add_f32_e32 v45, v45, v61
	s_waitcnt lgkmcnt(3)
	v_add_f32_e32 v46, v46, v62
	s_waitcnt lgkmcnt(2)
	v_add_f32_e32 v47, v47, v63
	s_waitcnt lgkmcnt(1)
	v_add_f32_e32 v48, v48, v64
	s_waitcnt lgkmcnt(0)
	v_add_f32_e32 v49, v49, v65
	v_cmp_eq_u32_e32 vcc, 0, v174
	s_and_saveexec_b64 s[58:59], vcc
	global_store_dword v167, v34, s[10:11]
	global_store_dword v167, v35, s[10:11] offset:4
	global_store_dword v167, v36, s[10:11] offset:8
	global_store_dword v167, v37, s[10:11] offset:12
	global_store_dword v167, v38, s[10:11] offset:32
	global_store_dword v167, v39, s[10:11] offset:36
	global_store_dword v167, v40, s[10:11] offset:40
	global_store_dword v167, v41, s[10:11] offset:44
	global_store_dword v167, v42, s[10:11] offset:64
	global_store_dword v167, v43, s[10:11] offset:68
	global_store_dword v167, v44, s[10:11] offset:72
	global_store_dword v167, v45, s[10:11] offset:76
	global_store_dword v167, v46, s[10:11] offset:96
	global_store_dword v167, v47, s[10:11] offset:100
	global_store_dword v167, v48, s[10:11] offset:104
	global_store_dword v167, v49, s[10:11] offset:108
	s_mov_b64 exec, -1
	s_waitcnt vmcnt(46)
	v_fmac_f32_e32 v66, v98, v175
	v_fmac_f32_e32 v82, v114, v176
	global_store_dword v162, v66, s[48:49]
	global_store_dword v162, v82, s[48:49] offset:128
	s_waitcnt vmcnt(46)
	v_fmac_f32_e32 v67, v99, v175
	v_fmac_f32_e32 v83, v115, v176
	global_store_dword v163, v67, s[48:49]
	global_store_dword v163, v83, s[48:49] offset:128
	s_waitcnt vmcnt(46)
	v_fmac_f32_e32 v68, v100, v175
	v_fmac_f32_e32 v84, v116, v176
	global_store_dword v164, v68, s[48:49]
	global_store_dword v164, v84, s[48:49] offset:128
	s_waitcnt vmcnt(46)
	v_fmac_f32_e32 v69, v101, v175
	v_fmac_f32_e32 v85, v117, v176
	global_store_dword v165, v69, s[48:49]
	global_store_dword v165, v85, s[48:49] offset:128
	s_add_u32 s48, s48, 0x8000
	s_addc_u32 s49, s49, 0
	s_waitcnt vmcnt(46)
	v_fmac_f32_e32 v70, v102, v175
	v_fmac_f32_e32 v86, v118, v176
	global_store_dword v162, v70, s[48:49]
	global_store_dword v162, v86, s[48:49] offset:128
	s_waitcnt vmcnt(46)
	v_fmac_f32_e32 v71, v103, v175
	v_fmac_f32_e32 v87, v119, v176
	global_store_dword v163, v71, s[48:49]
	global_store_dword v163, v87, s[48:49] offset:128
	s_waitcnt vmcnt(46)
	v_fmac_f32_e32 v72, v104, v175
	v_fmac_f32_e32 v88, v120, v176
	global_store_dword v164, v72, s[48:49]
	global_store_dword v164, v88, s[48:49] offset:128
	s_waitcnt vmcnt(46)
	v_fmac_f32_e32 v73, v105, v175
	v_fmac_f32_e32 v89, v121, v176
	global_store_dword v165, v73, s[48:49]
	global_store_dword v165, v89, s[48:49] offset:128
	s_add_u32 s48, s48, 0x8000
	s_addc_u32 s49, s49, 0
	s_waitcnt vmcnt(46)
	v_fmac_f32_e32 v74, v106, v175
	v_fmac_f32_e32 v90, v122, v176
	global_store_dword v162, v74, s[48:49]
	global_store_dword v162, v90, s[48:49] offset:128
	s_waitcnt vmcnt(46)
	v_fmac_f32_e32 v75, v107, v175
	v_fmac_f32_e32 v91, v123, v176
	global_store_dword v163, v75, s[48:49]
	global_store_dword v163, v91, s[48:49] offset:128
	s_waitcnt vmcnt(46)
	v_fmac_f32_e32 v76, v108, v175
	v_fmac_f32_e32 v92, v124, v176
	global_store_dword v164, v76, s[48:49]
	global_store_dword v164, v92, s[48:49] offset:128
	s_waitcnt vmcnt(46)
	v_fmac_f32_e32 v77, v109, v175
	v_fmac_f32_e32 v93, v125, v176
	global_store_dword v165, v77, s[48:49]
	global_store_dword v165, v93, s[48:49] offset:128
	s_add_u32 s48, s48, 0x8000
	s_addc_u32 s49, s49, 0
	s_waitcnt vmcnt(46)
	v_fmac_f32_e32 v78, v110, v175
	v_fmac_f32_e32 v94, v126, v176
	global_store_dword v162, v78, s[48:49]
	global_store_dword v162, v94, s[48:49] offset:128
	s_waitcnt vmcnt(46)
	v_fmac_f32_e32 v79, v111, v175
	v_fmac_f32_e32 v95, v127, v176
	global_store_dword v163, v79, s[48:49]
	global_store_dword v163, v95, s[48:49] offset:128
	s_waitcnt vmcnt(46)
	v_fmac_f32_e32 v80, v112, v175
	v_fmac_f32_e32 v96, v128, v176
	global_store_dword v164, v80, s[48:49]
	global_store_dword v164, v96, s[48:49] offset:128
	s_waitcnt vmcnt(46)
	v_fmac_f32_e32 v81, v113, v175
	v_fmac_f32_e32 v97, v129, v176
	global_store_dword v165, v81, s[48:49]
	global_store_dword v165, v97, s[48:49] offset:128
	s_sub_u32 s48, s48, 0x18000
	s_subb_u32 s49, s49, 0
	v_mul_f32_e32 v66, v66, v66
	v_fmac_f32_e32 v66, v82, v82
	v_mul_f32_e32 v67, v67, v67
	v_fmac_f32_e32 v67, v83, v83
	v_mul_f32_e32 v68, v68, v68
	v_fmac_f32_e32 v68, v84, v84
	v_mul_f32_e32 v69, v69, v69
	v_fmac_f32_e32 v69, v85, v85
	v_mul_f32_e32 v70, v70, v70
	v_fmac_f32_e32 v70, v86, v86
	v_mul_f32_e32 v71, v71, v71
	v_fmac_f32_e32 v71, v87, v87
	v_mul_f32_e32 v72, v72, v72
	v_fmac_f32_e32 v72, v88, v88
	v_mul_f32_e32 v73, v73, v73
	v_fmac_f32_e32 v73, v89, v89
	v_mul_f32_e32 v74, v74, v74
	v_fmac_f32_e32 v74, v90, v90
	v_mul_f32_e32 v75, v75, v75
	v_fmac_f32_e32 v75, v91, v91
	v_mul_f32_e32 v76, v76, v76
	v_fmac_f32_e32 v76, v92, v92
	v_mul_f32_e32 v77, v77, v77
	v_fmac_f32_e32 v77, v93, v93
	v_mul_f32_e32 v78, v78, v78
	v_fmac_f32_e32 v78, v94, v94
	v_mul_f32_e32 v79, v79, v79
	v_fmac_f32_e32 v79, v95, v95
	v_mul_f32_e32 v80, v80, v80
	v_fmac_f32_e32 v80, v96, v96
	v_mul_f32_e32 v81, v81, v81
	v_fmac_f32_e32 v81, v97, v97
	s_waitcnt lgkmcnt(0)
	ds_bpermute_b32 v82, v168, v66
	ds_bpermute_b32 v83, v168, v67
	ds_bpermute_b32 v84, v168, v68
	ds_bpermute_b32 v85, v168, v69
	ds_bpermute_b32 v86, v168, v70
	ds_bpermute_b32 v87, v168, v71
	ds_bpermute_b32 v88, v168, v72
	ds_bpermute_b32 v89, v168, v73
	s_waitcnt lgkmcnt(7)
	v_add_f32_e32 v66, v66, v82
	s_waitcnt lgkmcnt(6)
	v_add_f32_e32 v67, v67, v83
	s_waitcnt lgkmcnt(5)
	v_add_f32_e32 v68, v68, v84
	s_waitcnt lgkmcnt(4)
	v_add_f32_e32 v69, v69, v85
	s_waitcnt lgkmcnt(3)
	v_add_f32_e32 v70, v70, v86
	s_waitcnt lgkmcnt(2)
	v_add_f32_e32 v71, v71, v87
	s_waitcnt lgkmcnt(1)
	v_add_f32_e32 v72, v72, v88
	s_waitcnt lgkmcnt(0)
	v_add_f32_e32 v73, v73, v89
	ds_bpermute_b32 v82, v169, v66
	ds_bpermute_b32 v83, v169, v67
	ds_bpermute_b32 v84, v169, v68
	ds_bpermute_b32 v85, v169, v69
	ds_bpermute_b32 v86, v169, v70
	ds_bpermute_b32 v87, v169, v71
	ds_bpermute_b32 v88, v169, v72
	ds_bpermute_b32 v89, v169, v73
	s_waitcnt lgkmcnt(7)
	v_add_f32_e32 v66, v66, v82
	s_waitcnt lgkmcnt(6)
	v_add_f32_e32 v67, v67, v83
	s_waitcnt lgkmcnt(5)
	v_add_f32_e32 v68, v68, v84
	s_waitcnt lgkmcnt(4)
	v_add_f32_e32 v69, v69, v85
	s_waitcnt lgkmcnt(3)
	v_add_f32_e32 v70, v70, v86
	s_waitcnt lgkmcnt(2)
	v_add_f32_e32 v71, v71, v87
	s_waitcnt lgkmcnt(1)
	v_add_f32_e32 v72, v72, v88
	s_waitcnt lgkmcnt(0)
	v_add_f32_e32 v73, v73, v89
	ds_bpermute_b32 v82, v171, v66
	ds_bpermute_b32 v83, v171, v67
	ds_bpermute_b32 v84, v171, v68
	ds_bpermute_b32 v85, v171, v69
	ds_bpermute_b32 v86, v171, v70
	ds_bpermute_b32 v87, v171, v71
	ds_bpermute_b32 v88, v171, v72
	ds_bpermute_b32 v89, v171, v73
	s_waitcnt lgkmcnt(7)
	v_add_f32_e32 v66, v66, v82
	s_waitcnt lgkmcnt(6)
	v_add_f32_e32 v67, v67, v83
	s_waitcnt lgkmcnt(5)
	v_add_f32_e32 v68, v68, v84
	s_waitcnt lgkmcnt(4)
	v_add_f32_e32 v69, v69, v85
	s_waitcnt lgkmcnt(3)
	v_add_f32_e32 v70, v70, v86
	s_waitcnt lgkmcnt(2)
	v_add_f32_e32 v71, v71, v87
	s_waitcnt lgkmcnt(1)
	v_add_f32_e32 v72, v72, v88
	s_waitcnt lgkmcnt(0)
	v_add_f32_e32 v73, v73, v89
	ds_bpermute_b32 v82, v172, v66
	ds_bpermute_b32 v83, v172, v67
	ds_bpermute_b32 v84, v172, v68
	ds_bpermute_b32 v85, v172, v69
	ds_bpermute_b32 v86, v172, v70
	ds_bpermute_b32 v87, v172, v71
	ds_bpermute_b32 v88, v172, v72
	ds_bpermute_b32 v89, v172, v73
	s_waitcnt lgkmcnt(7)
	v_add_f32_e32 v66, v66, v82
	s_waitcnt lgkmcnt(6)
	v_add_f32_e32 v67, v67, v83
	s_waitcnt lgkmcnt(5)
	v_add_f32_e32 v68, v68, v84
	s_waitcnt lgkmcnt(4)
	v_add_f32_e32 v69, v69, v85
	s_waitcnt lgkmcnt(3)
	v_add_f32_e32 v70, v70, v86
	s_waitcnt lgkmcnt(2)
	v_add_f32_e32 v71, v71, v87
	s_waitcnt lgkmcnt(1)
	v_add_f32_e32 v72, v72, v88
	s_waitcnt lgkmcnt(0)
	v_add_f32_e32 v73, v73, v89
	ds_bpermute_b32 v82, v173, v66
	ds_bpermute_b32 v83, v173, v67
	ds_bpermute_b32 v84, v173, v68
	ds_bpermute_b32 v85, v173, v69
	ds_bpermute_b32 v86, v173, v70
	ds_bpermute_b32 v87, v173, v71
	ds_bpermute_b32 v88, v173, v72
	ds_bpermute_b32 v89, v173, v73
	s_waitcnt lgkmcnt(7)
	v_add_f32_e32 v66, v66, v82
	s_waitcnt lgkmcnt(6)
	v_add_f32_e32 v67, v67, v83
	s_waitcnt lgkmcnt(5)
	v_add_f32_e32 v68, v68, v84
	s_waitcnt lgkmcnt(4)
	v_add_f32_e32 v69, v69, v85
	s_waitcnt lgkmcnt(3)
	v_add_f32_e32 v70, v70, v86
	s_waitcnt lgkmcnt(2)
	v_add_f32_e32 v71, v71, v87
	s_waitcnt lgkmcnt(1)
	v_add_f32_e32 v72, v72, v88
	s_waitcnt lgkmcnt(0)
	v_add_f32_e32 v73, v73, v89
	ds_bpermute_b32 v90, v168, v74
	ds_bpermute_b32 v91, v168, v75
	ds_bpermute_b32 v92, v168, v76
	ds_bpermute_b32 v93, v168, v77
	ds_bpermute_b32 v94, v168, v78
	ds_bpermute_b32 v95, v168, v79
	ds_bpermute_b32 v96, v168, v80
	ds_bpermute_b32 v97, v168, v81
	s_waitcnt lgkmcnt(7)
	v_add_f32_e32 v74, v74, v90
	s_waitcnt lgkmcnt(6)
	v_add_f32_e32 v75, v75, v91
	s_waitcnt lgkmcnt(5)
	v_add_f32_e32 v76, v76, v92
	s_waitcnt lgkmcnt(4)
	v_add_f32_e32 v77, v77, v93
	s_waitcnt lgkmcnt(3)
	v_add_f32_e32 v78, v78, v94
	s_waitcnt lgkmcnt(2)
	v_add_f32_e32 v79, v79, v95
	s_waitcnt lgkmcnt(1)
	v_add_f32_e32 v80, v80, v96
	s_waitcnt lgkmcnt(0)
	v_add_f32_e32 v81, v81, v97
	ds_bpermute_b32 v90, v169, v74
	ds_bpermute_b32 v91, v169, v75
	ds_bpermute_b32 v92, v169, v76
	ds_bpermute_b32 v93, v169, v77
	ds_bpermute_b32 v94, v169, v78
	ds_bpermute_b32 v95, v169, v79
	ds_bpermute_b32 v96, v169, v80
	ds_bpermute_b32 v97, v169, v81
	s_waitcnt lgkmcnt(7)
	v_add_f32_e32 v74, v74, v90
	s_waitcnt lgkmcnt(6)
	v_add_f32_e32 v75, v75, v91
	s_waitcnt lgkmcnt(5)
	v_add_f32_e32 v76, v76, v92
	s_waitcnt lgkmcnt(4)
	v_add_f32_e32 v77, v77, v93
	s_waitcnt lgkmcnt(3)
	v_add_f32_e32 v78, v78, v94
	s_waitcnt lgkmcnt(2)
	v_add_f32_e32 v79, v79, v95
	s_waitcnt lgkmcnt(1)
	v_add_f32_e32 v80, v80, v96
	s_waitcnt lgkmcnt(0)
	v_add_f32_e32 v81, v81, v97
	ds_bpermute_b32 v90, v171, v74
	ds_bpermute_b32 v91, v171, v75
	ds_bpermute_b32 v92, v171, v76
	ds_bpermute_b32 v93, v171, v77
	ds_bpermute_b32 v94, v171, v78
	ds_bpermute_b32 v95, v171, v79
	ds_bpermute_b32 v96, v171, v80
	ds_bpermute_b32 v97, v171, v81
	s_waitcnt lgkmcnt(7)
	v_add_f32_e32 v74, v74, v90
	s_waitcnt lgkmcnt(6)
	v_add_f32_e32 v75, v75, v91
	s_waitcnt lgkmcnt(5)
	v_add_f32_e32 v76, v76, v92
	s_waitcnt lgkmcnt(4)
	v_add_f32_e32 v77, v77, v93
	s_waitcnt lgkmcnt(3)
	v_add_f32_e32 v78, v78, v94
	s_waitcnt lgkmcnt(2)
	v_add_f32_e32 v79, v79, v95
	s_waitcnt lgkmcnt(1)
	v_add_f32_e32 v80, v80, v96
	s_waitcnt lgkmcnt(0)
	v_add_f32_e32 v81, v81, v97
	ds_bpermute_b32 v90, v172, v74
	ds_bpermute_b32 v91, v172, v75
	ds_bpermute_b32 v92, v172, v76
	ds_bpermute_b32 v93, v172, v77
	ds_bpermute_b32 v94, v172, v78
	ds_bpermute_b32 v95, v172, v79
	ds_bpermute_b32 v96, v172, v80
	ds_bpermute_b32 v97, v172, v81
	s_waitcnt lgkmcnt(7)
	v_add_f32_e32 v74, v74, v90
	s_waitcnt lgkmcnt(6)
	v_add_f32_e32 v75, v75, v91
	s_waitcnt lgkmcnt(5)
	v_add_f32_e32 v76, v76, v92
	s_waitcnt lgkmcnt(4)
	v_add_f32_e32 v77, v77, v93
	s_waitcnt lgkmcnt(3)
	v_add_f32_e32 v78, v78, v94
	s_waitcnt lgkmcnt(2)
	v_add_f32_e32 v79, v79, v95
	s_waitcnt lgkmcnt(1)
	v_add_f32_e32 v80, v80, v96
	s_waitcnt lgkmcnt(0)
	v_add_f32_e32 v81, v81, v97
	ds_bpermute_b32 v90, v173, v74
	ds_bpermute_b32 v91, v173, v75
	ds_bpermute_b32 v92, v173, v76
	ds_bpermute_b32 v93, v173, v77
	ds_bpermute_b32 v94, v173, v78
	ds_bpermute_b32 v95, v173, v79
	ds_bpermute_b32 v96, v173, v80
	ds_bpermute_b32 v97, v173, v81
	s_waitcnt lgkmcnt(7)
	v_add_f32_e32 v74, v74, v90
	s_waitcnt lgkmcnt(6)
	v_add_f32_e32 v75, v75, v91
	s_waitcnt lgkmcnt(5)
	v_add_f32_e32 v76, v76, v92
	s_waitcnt lgkmcnt(4)
	v_add_f32_e32 v77, v77, v93
	s_waitcnt lgkmcnt(3)
	v_add_f32_e32 v78, v78, v94
	s_waitcnt lgkmcnt(2)
	v_add_f32_e32 v79, v79, v95
	s_waitcnt lgkmcnt(1)
	v_add_f32_e32 v80, v80, v96
	s_waitcnt lgkmcnt(0)
	v_add_f32_e32 v81, v81, v97
	v_cmp_eq_u32_e32 vcc, 0, v174
	s_and_saveexec_b64 s[58:59], vcc
	global_store_dword v167, v66, s[10:11] offset:128
	global_store_dword v167, v67, s[10:11] offset:132
	global_store_dword v167, v68, s[10:11] offset:136
	global_store_dword v167, v69, s[10:11] offset:140
	global_store_dword v167, v70, s[10:11] offset:160
	global_store_dword v167, v71, s[10:11] offset:164
	global_store_dword v167, v72, s[10:11] offset:168
	global_store_dword v167, v73, s[10:11] offset:172
	global_store_dword v167, v74, s[10:11] offset:192
	global_store_dword v167, v75, s[10:11] offset:196
	global_store_dword v167, v76, s[10:11] offset:200
	global_store_dword v167, v77, s[10:11] offset:204
	global_store_dword v167, v78, s[10:11] offset:224
	global_store_dword v167, v79, s[10:11] offset:228
	global_store_dword v167, v80, s[10:11] offset:232
	global_store_dword v167, v81, s[10:11] offset:236
	s_mov_b64 exec, -1
	v_readlane_b32 s2, v246, 14
	s_nop 0
	s_add_i32 s16, s16, s2
	s_branch .Lhw_outproj_tloop

.Lhw_ffndown_loop:
	v_mfma_f32_32x32x16_bf16 v[2:17], v[130:133], v[220:223], v[2:17]
	s_add_u32 m0, s65, 0x4000
	s_nop 0
	global_load_lds_dwordx4 v242, s[18:19]
	v_mfma_f32_32x32x16_bf16 v[34:49], v[146:149], v[220:223], v[34:49]
	s_add_u32 m0, s65, 0x5000
	ds_read_b128 v[220:223], v158 offset:16
	global_load_lds_dwordx4 v243, s[18:19]
	v_mfma_f32_32x32x16_bf16 v[2:17], v[134:137], v[224:227], v[2:17]
	s_add_u32 s62, s62, 128
	s_addc_u32 s63, s63, 0
	s_add_u32 s66, s66, 128
	s_addc_u32 s67, s67, 0
	v_mfma_f32_32x32x16_bf16 v[34:49], v[150:153], v[224:227], v[34:49]
	s_add_u32 m0, s65, 0x6000
	ds_read_b128 v[224:227], v159 offset:16
	global_load_lds_dwordx4 v160, s[62:63]
	v_mfma_f32_32x32x16_bf16 v[2:17], v[138:141], v[228:231], v[2:17]
	s_add_u32 m0, s65, 0x7000
	s_nop 0
	global_load_lds_dwordx4 v161, s[62:63]
	v_mfma_f32_32x32x16_bf16 v[34:49], v[212:215], v[228:231], v[34:49]
	s_add_u32 m0, s65, 0x8000
	ds_read_b128 v[228:231], v236 offset:16
	global_load_lds_dwordx4 v160, s[66:67]
	v_mfma_f32_32x32x16_bf16 v[2:17], v[142:145], v[232:235], v[2:17]
	s_add_u32 m0, s65, 0x9000
	s_nop 0
	global_load_lds_dwordx4 v161, s[66:67]
	v_mfma_f32_32x32x16_bf16 v[34:49], v[216:219], v[232:235], v[34:49]
	s_add_u32 m0, s65, 0xa000
	ds_read_b128 v[232:235], v237 offset:16
	global_load_lds_dwordx4 v242, s[66:67]
	s_waitcnt lgkmcnt(3)
	v_mfma_f32_32x32x16_bf16 v[18:33], v[130:133], v[220:223], v[18:33]
	s_add_u32 m0, s65, 0xb000
	s_nop 0
	global_load_lds_dwordx4 v243, s[66:67]
	v_mfma_f32_32x32x16_bf16 v[50:65], v[146:149], v[220:223], v[50:65]
	ds_read_b128 v[220:223], v158 offset:8208
	s_waitcnt lgkmcnt(3)
	v_mfma_f32_32x32x16_bf16 v[18:33], v[134:137], v[224:227], v[18:33]
	v_mfma_f32_32x32x16_bf16 v[50:65], v[150:153], v[224:227], v[50:65]
	ds_read_b128 v[224:227], v159 offset:8208
	s_waitcnt lgkmcnt(3)
	v_mfma_f32_32x32x16_bf16 v[18:33], v[138:141], v[228:231], v[18:33]
	v_mfma_f32_32x32x16_bf16 v[50:65], v[212:215], v[228:231], v[50:65]
	ds_read_b128 v[228:231], v236 offset:8208
	s_waitcnt lgkmcnt(3)
	v_mfma_f32_32x32x16_bf16 v[18:33], v[142:145], v[232:235], v[18:33]
	v_mfma_f32_32x32x16_bf16 v[50:65], v[216:219], v[232:235], v[50:65]
	ds_read_b128 v[232:235], v237 offset:8208
	s_waitcnt vmcnt(0) lgkmcnt(0)
	s_barrier
	v_mfma_f32_32x32x16_bf16 v[66:81], v[130:133], v[220:223], v[66:81]
	s_add_u32 s18, s18, 128
	s_addc_u32 s19, s19, 0
	v_mfma_f32_32x32x16_bf16 v[98:113], v[146:149], v[220:223], v[98:113]
	s_add_u32 m0, s65, 0x0
	ds_read_b128 v[220:223], v158 offset:16400
	global_load_lds_dwordx4 v242, s[62:63]
	v_mfma_f32_32x32x16_bf16 v[66:81], v[134:137], v[224:227], v[66:81]
	s_add_u32 m0, s65, 0x1000
	s_nop 0
	global_load_lds_dwordx4 v243, s[62:63]
	v_mfma_f32_32x32x16_bf16 v[98:113], v[150:153], v[224:227], v[98:113]
	s_add_u32 m0, s65, 0x2000
	ds_read_b128 v[224:227], v159 offset:16400
	global_load_lds_dwordx4 v160, s[18:19]
	v_mfma_f32_32x32x16_bf16 v[66:81], v[138:141], v[228:231], v[66:81]
	s_add_u32 m0, s65, 0x3000
	s_nop 0
	global_load_lds_dwordx4 v161, s[18:19]
	v_mfma_f32_32x32x16_bf16 v[98:113], v[212:215], v[228:231], v[98:113]
	ds_read_b128 v[228:231], v236 offset:16400
	v_mfma_f32_32x32x16_bf16 v[66:81], v[142:145], v[232:235], v[66:81]
	v_mfma_f32_32x32x16_bf16 v[98:113], v[216:219], v[232:235], v[98:113]
	ds_read_b128 v[232:235], v237 offset:16400
	s_waitcnt lgkmcnt(3)
	v_mfma_f32_32x32x16_bf16 v[82:97], v[130:133], v[220:223], v[82:97]
	ds_read_b128 v[130:133], v154 offset:32784
	v_mfma_f32_32x32x16_bf16 v[114:129], v[146:149], v[220:223], v[114:129]
	ds_read_b128 v[220:223], v158 offset:24592
	ds_read_b128 v[146:149], v154 offset:40976
	s_waitcnt lgkmcnt(5)
	v_mfma_f32_32x32x16_bf16 v[82:97], v[134:137], v[224:227], v[82:97]
	ds_read_b128 v[134:137], v155 offset:32784
	v_mfma_f32_32x32x16_bf16 v[114:129], v[150:153], v[224:227], v[114:129]
	ds_read_b128 v[224:227], v159 offset:24592
	ds_read_b128 v[150:153], v155 offset:40976
	s_waitcnt lgkmcnt(7)
	v_mfma_f32_32x32x16_bf16 v[82:97], v[138:141], v[228:231], v[82:97]
	ds_read_b128 v[138:141], v156 offset:32784
	v_mfma_f32_32x32x16_bf16 v[114:129], v[212:215], v[228:231], v[114:129]
	ds_read_b128 v[228:231], v236 offset:24592
	ds_read_b128 v[212:215], v156 offset:40976
	s_waitcnt lgkmcnt(9)
	v_mfma_f32_32x32x16_bf16 v[82:97], v[142:145], v[232:235], v[82:97]
	ds_read_b128 v[142:145], v157 offset:32784
	v_mfma_f32_32x32x16_bf16 v[114:129], v[216:219], v[232:235], v[114:129]
	ds_read_b128 v[232:235], v237 offset:24592
	ds_read_b128 v[216:219], v157 offset:40976
	s_waitcnt vmcnt(0) lgkmcnt(0)
	s_barrier
	s_sub_u32 s59, s59, 1
	s_cmp_lg_u32 s59, 0
	s_cbranch_scc1 .Lhw_ffndown_loop
	v_mfma_f32_32x32x16_bf16 v[2:17], v[130:133], v[220:223], v[2:17]
	s_add_u32 m0, s65, 0x4000
	s_nop 0
	global_load_lds_dwordx4 v242, s[18:19]
	v_mfma_f32_32x32x16_bf16 v[34:49], v[146:149], v[220:223], v[34:49]
	s_add_u32 m0, s65, 0x5000
	ds_read_b128 v[220:223], v158 offset:16
	global_load_lds_dwordx4 v243, s[18:19]
	v_mfma_f32_32x32x16_bf16 v[2:17], v[134:137], v[224:227], v[2:17]
	v_mfma_f32_32x32x16_bf16 v[34:49], v[150:153], v[224:227], v[34:49]
	ds_read_b128 v[224:227], v159 offset:16
	v_mfma_f32_32x32x16_bf16 v[2:17], v[138:141], v[228:231], v[2:17]
	v_mfma_f32_32x32x16_bf16 v[34:49], v[212:215], v[228:231], v[34:49]
	ds_read_b128 v[228:231], v236 offset:16
	v_mfma_f32_32x32x16_bf16 v[2:17], v[142:145], v[232:235], v[2:17]
	v_mfma_f32_32x32x16_bf16 v[34:49], v[216:219], v[232:235], v[34:49]
	ds_read_b128 v[232:235], v237 offset:16
	s_waitcnt lgkmcnt(3)
	v_mfma_f32_32x32x16_bf16 v[18:33], v[130:133], v[220:223], v[18:33]
	v_mfma_f32_32x32x16_bf16 v[50:65], v[146:149], v[220:223], v[50:65]
	ds_read_b128 v[220:223], v158 offset:8208
	s_waitcnt lgkmcnt(3)
	v_mfma_f32_32x32x16_bf16 v[18:33], v[134:137], v[224:227], v[18:33]
	v_mfma_f32_32x32x16_bf16 v[50:65], v[150:153], v[224:227], v[50:65]
	ds_read_b128 v[224:227], v159 offset:8208
	s_waitcnt lgkmcnt(3)
	v_mfma_f32_32x32x16_bf16 v[18:33], v[138:141], v[228:231], v[18:33]
	v_mfma_f32_32x32x16_bf16 v[50:65], v[212:215], v[228:231], v[50:65]
	ds_read_b128 v[228:231], v236 offset:8208
	s_waitcnt lgkmcnt(3)
	v_mfma_f32_32x32x16_bf16 v[18:33], v[142:145], v[232:235], v[18:33]
	v_mfma_f32_32x32x16_bf16 v[50:65], v[216:219], v[232:235], v[50:65]
	ds_read_b128 v[232:235], v237 offset:8208
	s_waitcnt vmcnt(0) lgkmcnt(0)
	s_barrier
	v_mfma_f32_32x32x16_bf16 v[66:81], v[130:133], v[220:223], v[66:81]
	v_mfma_f32_32x32x16_bf16 v[98:113], v[146:149], v[220:223], v[98:113]
	ds_read_b128 v[220:223], v158 offset:16400
	v_mfma_f32_32x32x16_bf16 v[66:81], v[134:137], v[224:227], v[66:81]
	v_mfma_f32_32x32x16_bf16 v[98:113], v[150:153], v[224:227], v[98:113]
	ds_read_b128 v[224:227], v159 offset:16400
	v_mfma_f32_32x32x16_bf16 v[66:81], v[138:141], v[228:231], v[66:81]
	v_mfma_f32_32x32x16_bf16 v[98:113], v[212:215], v[228:231], v[98:113]
	ds_read_b128 v[228:231], v236 offset:16400
	v_mfma_f32_32x32x16_bf16 v[66:81], v[142:145], v[232:235], v[66:81]
	v_mfma_f32_32x32x16_bf16 v[98:113], v[216:219], v[232:235], v[98:113]
	ds_read_b128 v[232:235], v237 offset:16400
	s_waitcnt lgkmcnt(3)
	v_mfma_f32_32x32x16_bf16 v[82:97], v[130:133], v[220:223], v[82:97]
	v_mfma_f32_32x32x16_bf16 v[114:129], v[146:149], v[220:223], v[114:129]
	s_waitcnt lgkmcnt(2)
	v_mfma_f32_32x32x16_bf16 v[82:97], v[134:137], v[224:227], v[82:97]
	v_mfma_f32_32x32x16_bf16 v[114:129], v[150:153], v[224:227], v[114:129]
	s_waitcnt lgkmcnt(1)
	v_mfma_f32_32x32x16_bf16 v[82:97], v[138:141], v[228:231], v[82:97]
	v_mfma_f32_32x32x16_bf16 v[114:129], v[212:215], v[228:231], v[114:129]
	s_waitcnt lgkmcnt(0)
	v_mfma_f32_32x32x16_bf16 v[82:97], v[142:145], v[232:235], v[82:97]
	v_mfma_f32_32x32x16_bf16 v[114:129], v[216:219], v[232:235], v[114:129]
	s_nop 7
	s_nop 7
	s_sub_i32 s2, s6, 0x1000
	s_ashr_i32 s2, s2, 11
	s_add_i32 s2, s2, 1
	s_max_i32 s2, s2, 0
	v_readlane_b32 s17, v246, 28
	s_nop 0
	s_add_i32 s2, s2, s17
	s_mul_i32 s2, s2, 0x9000
	s_lshl_b32 s17, s15, 2
	s_add_u32 s2, s2, s17
	s_add_u32 s60, s12, s2
	s_addc_u32 s61, s13, 0
	s_lshr_b32 s2, s15, 7
	s_mul_i32 s2, s2, 0x18000
	s_lshl_b32 s20, s6, 2
	s_add_u32 s2, s2, s20
	s_add_u32 s10, s44, s2
	s_addc_u32 s11, s45, 0
	s_lshl_b32 s2, s6, 12
	s_add_u32 s2, s2, s17
	s_add_u32 s48, s40, s2
	s_addc_u32 s49, s41, 0
	global_load_dword v175, v166, s[60:61]
	global_load_dword v176, v166, s[60:61] offset:128
	global_load_dword v130, v162, s[48:49]
	global_load_dword v212, v162, s[48:49] offset:128
	global_load_dword v131, v163, s[48:49]
	global_load_dword v213, v163, s[48:49] offset:128
	global_load_dword v132, v164, s[48:49]
	global_load_dword v214, v164, s[48:49] offset:128
	global_load_dword v133, v165, s[48:49]
	global_load_dword v215, v165, s[48:49] offset:128
	s_add_u32 s48, s48, 0x8000
	s_addc_u32 s49, s49, 0
	global_load_dword v134, v162, s[48:49]
	global_load_dword v216, v162, s[48:49] offset:128
	global_load_dword v135, v163, s[48:49]
	global_load_dword v217, v163, s[48:49] offset:128
	global_load_dword v136, v164, s[48:49]
	global_load_dword v218, v164, s[48:49] offset:128
	global_load_dword v137, v165, s[48:49]
	global_load_dword v219, v165, s[48:49] offset:128
	s_add_u32 s48, s48, 0x8000
	s_addc_u32 s49, s49, 0
	global_load_dword v138, v162, s[48:49]
	global_load_dword v220, v162, s[48:49] offset:128
	global_load_dword v139, v163, s[48:49]
	global_load_dword v221, v163, s[48:49] offset:128
	global_load_dword v140, v164, s[48:49]
	global_load_dword v222, v164, s[48:49] offset:128
	global_load_dword v141, v165, s[48:49]
	global_load_dword v223, v165, s[48:49] offset:128
	s_add_u32 s48, s48, 0x8000
	s_addc_u32 s49, s49, 0
	global_load_dword v142, v162, s[48:49]
	global_load_dword v224, v162, s[48:49] offset:128
	global_load_dword v143, v163, s[48:49]
	global_load_dword v225, v163, s[48:49] offset:128
	global_load_dword v144, v164, s[48:49]
	global_load_dword v226, v164, s[48:49] offset:128
	global_load_dword v145, v165, s[48:49]
	global_load_dword v227, v165, s[48:49] offset:128
	s_sub_u32 s48, s48, 0x18000
	s_subb_u32 s49, s49, 0
	s_waitcnt vmcnt(32)
	v_mul_f32_e32 v175, 0.5, v175
	v_mul_f32_e32 v176, 0.5, v176
	s_waitcnt vmcnt(30)
	v_fmac_f32_e32 v130, v2, v175
	v_fmac_f32_e32 v212, v18, v176
	global_store_dword v162, v130, s[48:49]
	global_store_dword v162, v212, s[48:49] offset:128
	s_waitcnt vmcnt(30)
	v_fmac_f32_e32 v131, v3, v175
	v_fmac_f32_e32 v213, v19, v176
	global_store_dword v163, v131, s[48:49]
	global_store_dword v163, v213, s[48:49] offset:128
	s_waitcnt vmcnt(30)
	v_fmac_f32_e32 v132, v4, v175
	v_fmac_f32_e32 v214, v20, v176
	global_store_dword v164, v132, s[48:49]
	global_store_dword v164, v214, s[48:49] offset:128
	s_waitcnt vmcnt(30)
	v_fmac_f32_e32 v133, v5, v175
	v_fmac_f32_e32 v215, v21, v176
	global_store_dword v165, v133, s[48:49]
	global_store_dword v165, v215, s[48:49] offset:128
	s_add_u32 s48, s48, 0x8000
	s_addc_u32 s49, s49, 0
	s_waitcnt vmcnt(30)
	v_fmac_f32_e32 v134, v6, v175
	v_fmac_f32_e32 v216, v22, v176
	global_store_dword v162, v134, s[48:49]
	global_store_dword v162, v216, s[48:49] offset:128
	s_waitcnt vmcnt(30)
	v_fmac_f32_e32 v135, v7, v175
	v_fmac_f32_e32 v217, v23, v176
	global_store_dword v163, v135, s[48:49]
	global_store_dword v163, v217, s[48:49] offset:128
	s_waitcnt vmcnt(30)
	v_fmac_f32_e32 v136, v8, v175
	v_fmac_f32_e32 v218, v24, v176
	global_store_dword v164, v136, s[48:49]
	global_store_dword v164, v218, s[48:49] offset:128
	s_waitcnt vmcnt(30)
	v_fmac_f32_e32 v137, v9, v175
	v_fmac_f32_e32 v219, v25, v176
	global_store_dword v165, v137, s[48:49]
	global_store_dword v165, v219, s[48:49] offset:128
	s_add_u32 s48, s48, 0x8000
	s_addc_u32 s49, s49, 0
	s_waitcnt vmcnt(30)
	v_fmac_f32_e32 v138, v10, v175
	v_fmac_f32_e32 v220, v26, v176
	global_store_dword v162, v138, s[48:49]
	global_store_dword v162, v220, s[48:49] offset:128
	s_waitcnt vmcnt(30)
	v_fmac_f32_e32 v139, v11, v175
	v_fmac_f32_e32 v221, v27, v176
	global_store_dword v163, v139, s[48:49]
	global_store_dword v163, v221, s[48:49] offset:128
	s_waitcnt vmcnt(30)
	v_fmac_f32_e32 v140, v12, v175
	v_fmac_f32_e32 v222, v28, v176
	global_store_dword v164, v140, s[48:49]
	global_store_dword v164, v222, s[48:49] offset:128
	s_waitcnt vmcnt(30)
	v_fmac_f32_e32 v141, v13, v175
	v_fmac_f32_e32 v223, v29, v176
	global_store_dword v165, v141, s[48:49]
	global_store_dword v165, v223, s[48:49] offset:128
	s_add_u32 s48, s48, 0x8000
	s_addc_u32 s49, s49, 0
	s_waitcnt vmcnt(30)
	v_fmac_f32_e32 v142, v14, v175
	v_fmac_f32_e32 v224, v30, v176
	global_store_dword v162, v142, s[48:49]
	global_store_dword v162, v224, s[48:49] offset:128
	s_waitcnt vmcnt(30)
	v_fmac_f32_e32 v143, v15, v175
	v_fmac_f32_e32 v225, v31, v176
	global_store_dword v163, v143, s[48:49]
	global_store_dword v163, v225, s[48:49] offset:128
	s_waitcnt vmcnt(30)
	v_fmac_f32_e32 v144, v16, v175
	v_fmac_f32_e32 v226, v32, v176
	global_store_dword v164, v144, s[48:49]
	global_store_dword v164, v226, s[48:49] offset:128
	s_waitcnt vmcnt(30)
	v_fmac_f32_e32 v145, v17, v175
	v_fmac_f32_e32 v227, v33, v176
	global_store_dword v165, v145, s[48:49]
	global_store_dword v165, v227, s[48:49] offset:128
	s_sub_u32 s48, s48, 0x18000
	s_subb_u32 s49, s49, 0
	s_add_u32 s48, s48, 0x20000
	s_addc_u32 s49, s49, 0
	global_load_dword v2, v162, s[48:49]
	global_load_dword v18, v162, s[48:49] offset:128
	global_load_dword v3, v163, s[48:49]
	global_load_dword v19, v163, s[48:49] offset:128
	global_load_dword v4, v164, s[48:49]
	global_load_dword v20, v164, s[48:49] offset:128
	global_load_dword v5, v165, s[48:49]
	global_load_dword v21, v165, s[48:49] offset:128
	s_add_u32 s48, s48, 0x8000
	s_addc_u32 s49, s49, 0
	global_load_dword v6, v162, s[48:49]
	global_load_dword v22, v162, s[48:49] offset:128
	global_load_dword v7, v163, s[48:49]
	global_load_dword v23, v163, s[48:49] offset:128
	global_load_dword v8, v164, s[48:49]
	global_load_dword v24, v164, s[48:49] offset:128
	global_load_dword v9, v165, s[48:49]
	global_load_dword v25, v165, s[48:49] offset:128
	s_add_u32 s48, s48, 0x8000
	s_addc_u32 s49, s49, 0
	global_load_dword v10, v162, s[48:49]
	global_load_dword v26, v162, s[48:49] offset:128
	global_load_dword v11, v163, s[48:49]
	global_load_dword v27, v163, s[48:49] offset:128
	global_load_dword v12, v164, s[48:49]
	global_load_dword v28, v164, s[48:49] offset:128
	global_load_dword v13, v165, s[48:49]
	global_load_dword v29, v165, s[48:49] offset:128
	s_add_u32 s48, s48, 0x8000
	s_addc_u32 s49, s49, 0
	global_load_dword v14, v162, s[48:49]
	global_load_dword v30, v162, s[48:49] offset:128
	global_load_dword v15, v163, s[48:49]
	global_load_dword v31, v163, s[48:49] offset:128
	global_load_dword v16, v164, s[48:49]
	global_load_dword v32, v164, s[48:49] offset:128
	global_load_dword v17, v165, s[48:49]
	global_load_dword v33, v165, s[48:49] offset:128
	s_sub_u32 s48, s48, 0x18000
	s_subb_u32 s49, s49, 0
	v_mul_f32_e32 v130, v130, v130
	v_fmac_f32_e32 v130, v212, v212
	v_mul_f32_e32 v131, v131, v131
	v_fmac_f32_e32 v131, v213, v213
	v_mul_f32_e32 v132, v132, v132
	v_fmac_f32_e32 v132, v214, v214
	v_mul_f32_e32 v133, v133, v133
	v_fmac_f32_e32 v133, v215, v215
	v_mul_f32_e32 v134, v134, v134
	v_fmac_f32_e32 v134, v216, v216
	v_mul_f32_e32 v135, v135, v135
	v_fmac_f32_e32 v135, v217, v217
	v_mul_f32_e32 v136, v136, v136
	v_fmac_f32_e32 v136, v218, v218
	v_mul_f32_e32 v137, v137, v137
	v_fmac_f32_e32 v137, v219, v219
	v_mul_f32_e32 v138, v138, v138
	v_fmac_f32_e32 v138, v220, v220
	v_mul_f32_e32 v139, v139, v139
	v_fmac_f32_e32 v139, v221, v221
	v_mul_f32_e32 v140, v140, v140
	v_fmac_f32_e32 v140, v222, v222
	v_mul_f32_e32 v141, v141, v141
	v_fmac_f32_e32 v141, v223, v223
	v_mul_f32_e32 v142, v142, v142
	v_fmac_f32_e32 v142, v224, v224
	v_mul_f32_e32 v143, v143, v143
	v_fmac_f32_e32 v143, v225, v225
	v_mul_f32_e32 v144, v144, v144
	v_fmac_f32_e32 v144, v226, v226
	v_mul_f32_e32 v145, v145, v145
	v_fmac_f32_e32 v145, v227, v227
	s_waitcnt lgkmcnt(0)
	ds_bpermute_b32 v212, v168, v130
	ds_bpermute_b32 v213, v168, v131
	ds_bpermute_b32 v214, v168, v132
	ds_bpermute_b32 v215, v168, v133
	ds_bpermute_b32 v216, v168, v134
	ds_bpermute_b32 v217, v168, v135
	ds_bpermute_b32 v218, v168, v136
	ds_bpermute_b32 v219, v168, v137
	s_waitcnt lgkmcnt(7)
	v_add_f32_e32 v130, v130, v212
	s_waitcnt lgkmcnt(6)
	v_add_f32_e32 v131, v131, v213
	s_waitcnt lgkmcnt(5)
	v_add_f32_e32 v132, v132, v214
	s_waitcnt lgkmcnt(4)
	v_add_f32_e32 v133, v133, v215
	s_waitcnt lgkmcnt(3)
	v_add_f32_e32 v134, v134, v216
	s_waitcnt lgkmcnt(2)
	v_add_f32_e32 v135, v135, v217
	s_waitcnt lgkmcnt(1)
	v_add_f32_e32 v136, v136, v218
	s_waitcnt lgkmcnt(0)
	v_add_f32_e32 v137, v137, v219
	ds_bpermute_b32 v212, v169, v130
	ds_bpermute_b32 v213, v169, v131
	ds_bpermute_b32 v214, v169, v132
	ds_bpermute_b32 v215, v169, v133
	ds_bpermute_b32 v216, v169, v134
	ds_bpermute_b32 v217, v169, v135
	ds_bpermute_b32 v218, v169, v136
	ds_bpermute_b32 v219, v169, v137
	s_waitcnt lgkmcnt(7)
	v_add_f32_e32 v130, v130, v212
	s_waitcnt lgkmcnt(6)
	v_add_f32_e32 v131, v131, v213
	s_waitcnt lgkmcnt(5)
	v_add_f32_e32 v132, v132, v214
	s_waitcnt lgkmcnt(4)
	v_add_f32_e32 v133, v133, v215
	s_waitcnt lgkmcnt(3)
	v_add_f32_e32 v134, v134, v216
	s_waitcnt lgkmcnt(2)
	v_add_f32_e32 v135, v135, v217
	s_waitcnt lgkmcnt(1)
	v_add_f32_e32 v136, v136, v218
	s_waitcnt lgkmcnt(0)
	v_add_f32_e32 v137, v137, v219
	ds_bpermute_b32 v212, v171, v130
	ds_bpermute_b32 v213, v171, v131
	ds_bpermute_b32 v214, v171, v132
	ds_bpermute_b32 v215, v171, v133
	ds_bpermute_b32 v216, v171, v134
	ds_bpermute_b32 v217, v171, v135
	ds_bpermute_b32 v218, v171, v136
	ds_bpermute_b32 v219, v171, v137
	s_waitcnt lgkmcnt(7)
	v_add_f32_e32 v130, v130, v212
	s_waitcnt lgkmcnt(6)
	v_add_f32_e32 v131, v131, v213
	s_waitcnt lgkmcnt(5)
	v_add_f32_e32 v132, v132, v214
	s_waitcnt lgkmcnt(4)
	v_add_f32_e32 v133, v133, v215
	s_waitcnt lgkmcnt(3)
	v_add_f32_e32 v134, v134, v216
	s_waitcnt lgkmcnt(2)
	v_add_f32_e32 v135, v135, v217
	s_waitcnt lgkmcnt(1)
	v_add_f32_e32 v136, v136, v218
	s_waitcnt lgkmcnt(0)
	v_add_f32_e32 v137, v137, v219
	ds_bpermute_b32 v212, v172, v130
	ds_bpermute_b32 v213, v172, v131
	ds_bpermute_b32 v214, v172, v132
	ds_bpermute_b32 v215, v172, v133
	ds_bpermute_b32 v216, v172, v134
	ds_bpermute_b32 v217, v172, v135
	ds_bpermute_b32 v218, v172, v136
	ds_bpermute_b32 v219, v172, v137
	s_waitcnt lgkmcnt(7)
	v_add_f32_e32 v130, v130, v212
	s_waitcnt lgkmcnt(6)
	v_add_f32_e32 v131, v131, v213
	s_waitcnt lgkmcnt(5)
	v_add_f32_e32 v132, v132, v214
	s_waitcnt lgkmcnt(4)
	v_add_f32_e32 v133, v133, v215
	s_waitcnt lgkmcnt(3)
	v_add_f32_e32 v134, v134, v216
	s_waitcnt lgkmcnt(2)
	v_add_f32_e32 v135, v135, v217
	s_waitcnt lgkmcnt(1)
	v_add_f32_e32 v136, v136, v218
	s_waitcnt lgkmcnt(0)
	v_add_f32_e32 v137, v137, v219
	ds_bpermute_b32 v212, v173, v130
	ds_bpermute_b32 v213, v173, v131
	ds_bpermute_b32 v214, v173, v132
	ds_bpermute_b32 v215, v173, v133
	ds_bpermute_b32 v216, v173, v134
	ds_bpermute_b32 v217, v173, v135
	ds_bpermute_b32 v218, v173, v136
	ds_bpermute_b32 v219, v173, v137
	s_waitcnt lgkmcnt(7)
	v_add_f32_e32 v130, v130, v212
	s_waitcnt lgkmcnt(6)
	v_add_f32_e32 v131, v131, v213
	s_waitcnt lgkmcnt(5)
	v_add_f32_e32 v132, v132, v214
	s_waitcnt lgkmcnt(4)
	v_add_f32_e32 v133, v133, v215
	s_waitcnt lgkmcnt(3)
	v_add_f32_e32 v134, v134, v216
	s_waitcnt lgkmcnt(2)
	v_add_f32_e32 v135, v135, v217
	s_waitcnt lgkmcnt(1)
	v_add_f32_e32 v136, v136, v218
	s_waitcnt lgkmcnt(0)
	v_add_f32_e32 v137, v137, v219
	ds_bpermute_b32 v220, v168, v138
	ds_bpermute_b32 v221, v168, v139
	ds_bpermute_b32 v222, v168, v140
	ds_bpermute_b32 v223, v168, v141
	ds_bpermute_b32 v224, v168, v142
	ds_bpermute_b32 v225, v168, v143
	ds_bpermute_b32 v226, v168, v144
	ds_bpermute_b32 v227, v168, v145
	s_waitcnt lgkmcnt(7)
	v_add_f32_e32 v138, v138, v220
	s_waitcnt lgkmcnt(6)
	v_add_f32_e32 v139, v139, v221
	s_waitcnt lgkmcnt(5)
	v_add_f32_e32 v140, v140, v222
	s_waitcnt lgkmcnt(4)
	v_add_f32_e32 v141, v141, v223
	s_waitcnt lgkmcnt(3)
	v_add_f32_e32 v142, v142, v224
	s_waitcnt lgkmcnt(2)
	v_add_f32_e32 v143, v143, v225
	s_waitcnt lgkmcnt(1)
	v_add_f32_e32 v144, v144, v226
	s_waitcnt lgkmcnt(0)
	v_add_f32_e32 v145, v145, v227
	ds_bpermute_b32 v220, v169, v138
	ds_bpermute_b32 v221, v169, v139
	ds_bpermute_b32 v222, v169, v140
	ds_bpermute_b32 v223, v169, v141
	ds_bpermute_b32 v224, v169, v142
	ds_bpermute_b32 v225, v169, v143
	ds_bpermute_b32 v226, v169, v144
	ds_bpermute_b32 v227, v169, v145
	s_waitcnt lgkmcnt(7)
	v_add_f32_e32 v138, v138, v220
	s_waitcnt lgkmcnt(6)
	v_add_f32_e32 v139, v139, v221
	s_waitcnt lgkmcnt(5)
	v_add_f32_e32 v140, v140, v222
	s_waitcnt lgkmcnt(4)
	v_add_f32_e32 v141, v141, v223
	s_waitcnt lgkmcnt(3)
	v_add_f32_e32 v142, v142, v224
	s_waitcnt lgkmcnt(2)
	v_add_f32_e32 v143, v143, v225
	s_waitcnt lgkmcnt(1)
	v_add_f32_e32 v144, v144, v226
	s_waitcnt lgkmcnt(0)
	v_add_f32_e32 v145, v145, v227
	ds_bpermute_b32 v220, v171, v138
	ds_bpermute_b32 v221, v171, v139
	ds_bpermute_b32 v222, v171, v140
	ds_bpermute_b32 v223, v171, v141
	ds_bpermute_b32 v224, v171, v142
	ds_bpermute_b32 v225, v171, v143
	ds_bpermute_b32 v226, v171, v144
	ds_bpermute_b32 v227, v171, v145
	s_waitcnt lgkmcnt(7)
	v_add_f32_e32 v138, v138, v220
	s_waitcnt lgkmcnt(6)
	v_add_f32_e32 v139, v139, v221
	s_waitcnt lgkmcnt(5)
	v_add_f32_e32 v140, v140, v222
	s_waitcnt lgkmcnt(4)
	v_add_f32_e32 v141, v141, v223
	s_waitcnt lgkmcnt(3)
	v_add_f32_e32 v142, v142, v224
	s_waitcnt lgkmcnt(2)
	v_add_f32_e32 v143, v143, v225
	s_waitcnt lgkmcnt(1)
	v_add_f32_e32 v144, v144, v226
	s_waitcnt lgkmcnt(0)
	v_add_f32_e32 v145, v145, v227
	ds_bpermute_b32 v220, v172, v138
	ds_bpermute_b32 v221, v172, v139
	ds_bpermute_b32 v222, v172, v140
	ds_bpermute_b32 v223, v172, v141
	ds_bpermute_b32 v224, v172, v142
	ds_bpermute_b32 v225, v172, v143
	ds_bpermute_b32 v226, v172, v144
	ds_bpermute_b32 v227, v172, v145
	s_waitcnt lgkmcnt(7)
	v_add_f32_e32 v138, v138, v220
	s_waitcnt lgkmcnt(6)
	v_add_f32_e32 v139, v139, v221
	s_waitcnt lgkmcnt(5)
	v_add_f32_e32 v140, v140, v222
	s_waitcnt lgkmcnt(4)
	v_add_f32_e32 v141, v141, v223
	s_waitcnt lgkmcnt(3)
	v_add_f32_e32 v142, v142, v224
	s_waitcnt lgkmcnt(2)
	v_add_f32_e32 v143, v143, v225
	s_waitcnt lgkmcnt(1)
	v_add_f32_e32 v144, v144, v226
	s_waitcnt lgkmcnt(0)
	v_add_f32_e32 v145, v145, v227
	ds_bpermute_b32 v220, v173, v138
	ds_bpermute_b32 v221, v173, v139
	ds_bpermute_b32 v222, v173, v140
	ds_bpermute_b32 v223, v173, v141
	ds_bpermute_b32 v224, v173, v142
	ds_bpermute_b32 v225, v173, v143
	ds_bpermute_b32 v226, v173, v144
	ds_bpermute_b32 v227, v173, v145
	s_waitcnt lgkmcnt(7)
	v_add_f32_e32 v138, v138, v220
	s_waitcnt lgkmcnt(6)
	v_add_f32_e32 v139, v139, v221
	s_waitcnt lgkmcnt(5)
	v_add_f32_e32 v140, v140, v222
	s_waitcnt lgkmcnt(4)
	v_add_f32_e32 v141, v141, v223
	s_waitcnt lgkmcnt(3)
	v_add_f32_e32 v142, v142, v224
	s_waitcnt lgkmcnt(2)
	v_add_f32_e32 v143, v143, v225
	s_waitcnt lgkmcnt(1)
	v_add_f32_e32 v144, v144, v226
	s_waitcnt lgkmcnt(0)
	v_add_f32_e32 v145, v145, v227
	v_cmp_eq_u32_e32 vcc, 0, v174
	s_and_saveexec_b64 s[58:59], vcc
	global_store_dword v167, v130, s[10:11]
	global_store_dword v167, v131, s[10:11] offset:4
	global_store_dword v167, v132, s[10:11] offset:8
	global_store_dword v167, v133, s[10:11] offset:12
	global_store_dword v167, v134, s[10:11] offset:32
	global_store_dword v167, v135, s[10:11] offset:36
	global_store_dword v167, v136, s[10:11] offset:40
	global_store_dword v167, v137, s[10:11] offset:44
	global_store_dword v167, v138, s[10:11] offset:64
	global_store_dword v167, v139, s[10:11] offset:68
	global_store_dword v167, v140, s[10:11] offset:72
	global_store_dword v167, v141, s[10:11] offset:76
	global_store_dword v167, v142, s[10:11] offset:96
	global_store_dword v167, v143, s[10:11] offset:100
	global_store_dword v167, v144, s[10:11] offset:104
	global_store_dword v167, v145, s[10:11] offset:108
	s_mov_b64 exec, -1
	s_waitcnt vmcnt(46)
	v_fmac_f32_e32 v2, v34, v175
	v_fmac_f32_e32 v18, v50, v176
	global_store_dword v162, v2, s[48:49]
	global_store_dword v162, v18, s[48:49] offset:128
	s_waitcnt vmcnt(46)
	v_fmac_f32_e32 v3, v35, v175
	v_fmac_f32_e32 v19, v51, v176
	global_store_dword v163, v3, s[48:49]
	global_store_dword v163, v19, s[48:49] offset:128
	s_waitcnt vmcnt(46)
	v_fmac_f32_e32 v4, v36, v175
	v_fmac_f32_e32 v20, v52, v176
	global_store_dword v164, v4, s[48:49]
	global_store_dword v164, v20, s[48:49] offset:128
	s_waitcnt vmcnt(46)
	v_fmac_f32_e32 v5, v37, v175
	v_fmac_f32_e32 v21, v53, v176
	global_store_dword v165, v5, s[48:49]
	global_store_dword v165, v21, s[48:49] offset:128
	s_add_u32 s48, s48, 0x8000
	s_addc_u32 s49, s49, 0
	s_waitcnt vmcnt(46)
	v_fmac_f32_e32 v6, v38, v175
	v_fmac_f32_e32 v22, v54, v176
	global_store_dword v162, v6, s[48:49]
	global_store_dword v162, v22, s[48:49] offset:128
	s_waitcnt vmcnt(46)
	v_fmac_f32_e32 v7, v39, v175
	v_fmac_f32_e32 v23, v55, v176
	global_store_dword v163, v7, s[48:49]
	global_store_dword v163, v23, s[48:49] offset:128
	s_waitcnt vmcnt(46)
	v_fmac_f32_e32 v8, v40, v175
	v_fmac_f32_e32 v24, v56, v176
	global_store_dword v164, v8, s[48:49]
	global_store_dword v164, v24, s[48:49] offset:128
	s_waitcnt vmcnt(46)
	v_fmac_f32_e32 v9, v41, v175
	v_fmac_f32_e32 v25, v57, v176
	global_store_dword v165, v9, s[48:49]
	global_store_dword v165, v25, s[48:49] offset:128
	s_add_u32 s48, s48, 0x8000
	s_addc_u32 s49, s49, 0
	s_waitcnt vmcnt(46)
	v_fmac_f32_e32 v10, v42, v175
	v_fmac_f32_e32 v26, v58, v176
	global_store_dword v162, v10, s[48:49]
	global_store_dword v162, v26, s[48:49] offset:128
	s_waitcnt vmcnt(46)
	v_fmac_f32_e32 v11, v43, v175
	v_fmac_f32_e32 v27, v59, v176
	global_store_dword v163, v11, s[48:49]
	global_store_dword v163, v27, s[48:49] offset:128
	s_waitcnt vmcnt(46)
	v_fmac_f32_e32 v12, v44, v175
	v_fmac_f32_e32 v28, v60, v176
	global_store_dword v164, v12, s[48:49]
	global_store_dword v164, v28, s[48:49] offset:128
	s_waitcnt vmcnt(46)
	v_fmac_f32_e32 v13, v45, v175
	v_fmac_f32_e32 v29, v61, v176
	global_store_dword v165, v13, s[48:49]
	global_store_dword v165, v29, s[48:49] offset:128
	s_add_u32 s48, s48, 0x8000
	s_addc_u32 s49, s49, 0
	s_waitcnt vmcnt(46)
	v_fmac_f32_e32 v14, v46, v175
	v_fmac_f32_e32 v30, v62, v176
	global_store_dword v162, v14, s[48:49]
	global_store_dword v162, v30, s[48:49] offset:128
	s_waitcnt vmcnt(46)
	v_fmac_f32_e32 v15, v47, v175
	v_fmac_f32_e32 v31, v63, v176
	global_store_dword v163, v15, s[48:49]
	global_store_dword v163, v31, s[48:49] offset:128
	s_waitcnt vmcnt(46)
	v_fmac_f32_e32 v16, v48, v175
	v_fmac_f32_e32 v32, v64, v176
	global_store_dword v164, v16, s[48:49]
	global_store_dword v164, v32, s[48:49] offset:128
	s_waitcnt vmcnt(46)
	v_fmac_f32_e32 v17, v49, v175
	v_fmac_f32_e32 v33, v65, v176
	global_store_dword v165, v17, s[48:49]
	global_store_dword v165, v33, s[48:49] offset:128
	s_sub_u32 s48, s48, 0x18000
	s_subb_u32 s49, s49, 0
	s_sub_u32 s48, s48, 0x1fe00
	s_subb_u32 s49, s49, 0
	s_add_u32 s60, s60, 0x200
	s_addc_u32 s61, s61, 0
	global_load_dword v175, v166, s[60:61]
	global_load_dword v176, v166, s[60:61] offset:128
	global_load_dword v34, v162, s[48:49]
	global_load_dword v50, v162, s[48:49] offset:128
	global_load_dword v35, v163, s[48:49]
	global_load_dword v51, v163, s[48:49] offset:128
	global_load_dword v36, v164, s[48:49]
	global_load_dword v52, v164, s[48:49] offset:128
	global_load_dword v37, v165, s[48:49]
	global_load_dword v53, v165, s[48:49] offset:128
	s_add_u32 s48, s48, 0x8000
	s_addc_u32 s49, s49, 0
	global_load_dword v38, v162, s[48:49]
	global_load_dword v54, v162, s[48:49] offset:128
	global_load_dword v39, v163, s[48:49]
	global_load_dword v55, v163, s[48:49] offset:128
	global_load_dword v40, v164, s[48:49]
	global_load_dword v56, v164, s[48:49] offset:128
	global_load_dword v41, v165, s[48:49]
	global_load_dword v57, v165, s[48:49] offset:128
	s_add_u32 s48, s48, 0x8000
	s_addc_u32 s49, s49, 0
	global_load_dword v42, v162, s[48:49]
	global_load_dword v58, v162, s[48:49] offset:128
	global_load_dword v43, v163, s[48:49]
	global_load_dword v59, v163, s[48:49] offset:128
	global_load_dword v44, v164, s[48:49]
	global_load_dword v60, v164, s[48:49] offset:128
	global_load_dword v45, v165, s[48:49]
	global_load_dword v61, v165, s[48:49] offset:128
	s_add_u32 s48, s48, 0x8000
	s_addc_u32 s49, s49, 0
	global_load_dword v46, v162, s[48:49]
	global_load_dword v62, v162, s[48:49] offset:128
	global_load_dword v47, v163, s[48:49]
	global_load_dword v63, v163, s[48:49] offset:128
	global_load_dword v48, v164, s[48:49]
	global_load_dword v64, v164, s[48:49] offset:128
	global_load_dword v49, v165, s[48:49]
	global_load_dword v65, v165, s[48:49] offset:128
	s_sub_u32 s48, s48, 0x18000
	s_subb_u32 s49, s49, 0
	v_mul_f32_e32 v2, v2, v2
	v_fmac_f32_e32 v2, v18, v18
	v_mul_f32_e32 v3, v3, v3
	v_fmac_f32_e32 v3, v19, v19
	v_mul_f32_e32 v4, v4, v4
	v_fmac_f32_e32 v4, v20, v20
	v_mul_f32_e32 v5, v5, v5
	v_fmac_f32_e32 v5, v21, v21
	v_mul_f32_e32 v6, v6, v6
	v_fmac_f32_e32 v6, v22, v22
	v_mul_f32_e32 v7, v7, v7
	v_fmac_f32_e32 v7, v23, v23
	v_mul_f32_e32 v8, v8, v8
	v_fmac_f32_e32 v8, v24, v24
	v_mul_f32_e32 v9, v9, v9
	v_fmac_f32_e32 v9, v25, v25
	v_mul_f32_e32 v10, v10, v10
	v_fmac_f32_e32 v10, v26, v26
	v_mul_f32_e32 v11, v11, v11
	v_fmac_f32_e32 v11, v27, v27
	v_mul_f32_e32 v12, v12, v12
	v_fmac_f32_e32 v12, v28, v28
	v_mul_f32_e32 v13, v13, v13
	v_fmac_f32_e32 v13, v29, v29
	v_mul_f32_e32 v14, v14, v14
	v_fmac_f32_e32 v14, v30, v30
	v_mul_f32_e32 v15, v15, v15
	v_fmac_f32_e32 v15, v31, v31
	v_mul_f32_e32 v16, v16, v16
	v_fmac_f32_e32 v16, v32, v32
	v_mul_f32_e32 v17, v17, v17
	v_fmac_f32_e32 v17, v33, v33
	s_waitcnt lgkmcnt(0)
	ds_bpermute_b32 v18, v168, v2
	ds_bpermute_b32 v19, v168, v3
	ds_bpermute_b32 v20, v168, v4
	ds_bpermute_b32 v21, v168, v5
	ds_bpermute_b32 v22, v168, v6
	ds_bpermute_b32 v23, v168, v7
	ds_bpermute_b32 v24, v168, v8
	ds_bpermute_b32 v25, v168, v9
	s_waitcnt lgkmcnt(7)
	v_add_f32_e32 v2, v2, v18
	s_waitcnt lgkmcnt(6)
	v_add_f32_e32 v3, v3, v19
	s_waitcnt lgkmcnt(5)
	v_add_f32_e32 v4, v4, v20
	s_waitcnt lgkmcnt(4)
	v_add_f32_e32 v5, v5, v21
	s_waitcnt lgkmcnt(3)
	v_add_f32_e32 v6, v6, v22
	s_waitcnt lgkmcnt(2)
	v_add_f32_e32 v7, v7, v23
	s_waitcnt lgkmcnt(1)
	v_add_f32_e32 v8, v8, v24
	s_waitcnt lgkmcnt(0)
	v_add_f32_e32 v9, v9, v25
	ds_bpermute_b32 v18, v169, v2
	ds_bpermute_b32 v19, v169, v3
	ds_bpermute_b32 v20, v169, v4
	ds_bpermute_b32 v21, v169, v5
	ds_bpermute_b32 v22, v169, v6
	ds_bpermute_b32 v23, v169, v7
	ds_bpermute_b32 v24, v169, v8
	ds_bpermute_b32 v25, v169, v9
	s_waitcnt lgkmcnt(7)
	v_add_f32_e32 v2, v2, v18
	s_waitcnt lgkmcnt(6)
	v_add_f32_e32 v3, v3, v19
	s_waitcnt lgkmcnt(5)
	v_add_f32_e32 v4, v4, v20
	s_waitcnt lgkmcnt(4)
	v_add_f32_e32 v5, v5, v21
	s_waitcnt lgkmcnt(3)
	v_add_f32_e32 v6, v6, v22
	s_waitcnt lgkmcnt(2)
	v_add_f32_e32 v7, v7, v23
	s_waitcnt lgkmcnt(1)
	v_add_f32_e32 v8, v8, v24
	s_waitcnt lgkmcnt(0)
	v_add_f32_e32 v9, v9, v25
	ds_bpermute_b32 v18, v171, v2
	ds_bpermute_b32 v19, v171, v3
	ds_bpermute_b32 v20, v171, v4
	ds_bpermute_b32 v21, v171, v5
	ds_bpermute_b32 v22, v171, v6
	ds_bpermute_b32 v23, v171, v7
	ds_bpermute_b32 v24, v171, v8
	ds_bpermute_b32 v25, v171, v9
	s_waitcnt lgkmcnt(7)
	v_add_f32_e32 v2, v2, v18
	s_waitcnt lgkmcnt(6)
	v_add_f32_e32 v3, v3, v19
	s_waitcnt lgkmcnt(5)
	v_add_f32_e32 v4, v4, v20
	s_waitcnt lgkmcnt(4)
	v_add_f32_e32 v5, v5, v21
	s_waitcnt lgkmcnt(3)
	v_add_f32_e32 v6, v6, v22
	s_waitcnt lgkmcnt(2)
	v_add_f32_e32 v7, v7, v23
	s_waitcnt lgkmcnt(1)
	v_add_f32_e32 v8, v8, v24
	s_waitcnt lgkmcnt(0)
	v_add_f32_e32 v9, v9, v25
	ds_bpermute_b32 v18, v172, v2
	ds_bpermute_b32 v19, v172, v3
	ds_bpermute_b32 v20, v172, v4
	ds_bpermute_b32 v21, v172, v5
	ds_bpermute_b32 v22, v172, v6
	ds_bpermute_b32 v23, v172, v7
	ds_bpermute_b32 v24, v172, v8
	ds_bpermute_b32 v25, v172, v9
	s_waitcnt lgkmcnt(7)
	v_add_f32_e32 v2, v2, v18
	s_waitcnt lgkmcnt(6)
	v_add_f32_e32 v3, v3, v19
	s_waitcnt lgkmcnt(5)
	v_add_f32_e32 v4, v4, v20
	s_waitcnt lgkmcnt(4)
	v_add_f32_e32 v5, v5, v21
	s_waitcnt lgkmcnt(3)
	v_add_f32_e32 v6, v6, v22
	s_waitcnt lgkmcnt(2)
	v_add_f32_e32 v7, v7, v23
	s_waitcnt lgkmcnt(1)
	v_add_f32_e32 v8, v8, v24
	s_waitcnt lgkmcnt(0)
	v_add_f32_e32 v9, v9, v25
	ds_bpermute_b32 v18, v173, v2
	ds_bpermute_b32 v19, v173, v3
	ds_bpermute_b32 v20, v173, v4
	ds_bpermute_b32 v21, v173, v5
	ds_bpermute_b32 v22, v173, v6
	ds_bpermute_b32 v23, v173, v7
	ds_bpermute_b32 v24, v173, v8
	ds_bpermute_b32 v25, v173, v9
	s_waitcnt lgkmcnt(7)
	v_add_f32_e32 v2, v2, v18
	s_waitcnt lgkmcnt(6)
	v_add_f32_e32 v3, v3, v19
	s_waitcnt lgkmcnt(5)
	v_add_f32_e32 v4, v4, v20
	s_waitcnt lgkmcnt(4)
	v_add_f32_e32 v5, v5, v21
	s_waitcnt lgkmcnt(3)
	v_add_f32_e32 v6, v6, v22
	s_waitcnt lgkmcnt(2)
	v_add_f32_e32 v7, v7, v23
	s_waitcnt lgkmcnt(1)
	v_add_f32_e32 v8, v8, v24
	s_waitcnt lgkmcnt(0)
	v_add_f32_e32 v9, v9, v25
	ds_bpermute_b32 v26, v168, v10
	ds_bpermute_b32 v27, v168, v11
	ds_bpermute_b32 v28, v168, v12
	ds_bpermute_b32 v29, v168, v13
	ds_bpermute_b32 v30, v168, v14
	ds_bpermute_b32 v31, v168, v15
	ds_bpermute_b32 v32, v168, v16
	ds_bpermute_b32 v33, v168, v17
	s_waitcnt lgkmcnt(7)
	v_add_f32_e32 v10, v10, v26
	s_waitcnt lgkmcnt(6)
	v_add_f32_e32 v11, v11, v27
	s_waitcnt lgkmcnt(5)
	v_add_f32_e32 v12, v12, v28
	s_waitcnt lgkmcnt(4)
	v_add_f32_e32 v13, v13, v29
	s_waitcnt lgkmcnt(3)
	v_add_f32_e32 v14, v14, v30
	s_waitcnt lgkmcnt(2)
	v_add_f32_e32 v15, v15, v31
	s_waitcnt lgkmcnt(1)
	v_add_f32_e32 v16, v16, v32
	s_waitcnt lgkmcnt(0)
	v_add_f32_e32 v17, v17, v33
	ds_bpermute_b32 v26, v169, v10
	ds_bpermute_b32 v27, v169, v11
	ds_bpermute_b32 v28, v169, v12
	ds_bpermute_b32 v29, v169, v13
	ds_bpermute_b32 v30, v169, v14
	ds_bpermute_b32 v31, v169, v15
	ds_bpermute_b32 v32, v169, v16
	ds_bpermute_b32 v33, v169, v17
	s_waitcnt lgkmcnt(7)
	v_add_f32_e32 v10, v10, v26
	s_waitcnt lgkmcnt(6)
	v_add_f32_e32 v11, v11, v27
	s_waitcnt lgkmcnt(5)
	v_add_f32_e32 v12, v12, v28
	s_waitcnt lgkmcnt(4)
	v_add_f32_e32 v13, v13, v29
	s_waitcnt lgkmcnt(3)
	v_add_f32_e32 v14, v14, v30
	s_waitcnt lgkmcnt(2)
	v_add_f32_e32 v15, v15, v31
	s_waitcnt lgkmcnt(1)
	v_add_f32_e32 v16, v16, v32
	s_waitcnt lgkmcnt(0)
	v_add_f32_e32 v17, v17, v33
	ds_bpermute_b32 v26, v171, v10
	ds_bpermute_b32 v27, v171, v11
	ds_bpermute_b32 v28, v171, v12
	ds_bpermute_b32 v29, v171, v13
	ds_bpermute_b32 v30, v171, v14
	ds_bpermute_b32 v31, v171, v15
	ds_bpermute_b32 v32, v171, v16
	ds_bpermute_b32 v33, v171, v17
	s_waitcnt lgkmcnt(7)
	v_add_f32_e32 v10, v10, v26
	s_waitcnt lgkmcnt(6)
	v_add_f32_e32 v11, v11, v27
	s_waitcnt lgkmcnt(5)
	v_add_f32_e32 v12, v12, v28
	s_waitcnt lgkmcnt(4)
	v_add_f32_e32 v13, v13, v29
	s_waitcnt lgkmcnt(3)
	v_add_f32_e32 v14, v14, v30
	s_waitcnt lgkmcnt(2)
	v_add_f32_e32 v15, v15, v31
	s_waitcnt lgkmcnt(1)
	v_add_f32_e32 v16, v16, v32
	s_waitcnt lgkmcnt(0)
	v_add_f32_e32 v17, v17, v33
	ds_bpermute_b32 v26, v172, v10
	ds_bpermute_b32 v27, v172, v11
	ds_bpermute_b32 v28, v172, v12
	ds_bpermute_b32 v29, v172, v13
	ds_bpermute_b32 v30, v172, v14
	ds_bpermute_b32 v31, v172, v15
	ds_bpermute_b32 v32, v172, v16
	ds_bpermute_b32 v33, v172, v17
	s_waitcnt lgkmcnt(7)
	v_add_f32_e32 v10, v10, v26
	s_waitcnt lgkmcnt(6)
	v_add_f32_e32 v11, v11, v27
	s_waitcnt lgkmcnt(5)
	v_add_f32_e32 v12, v12, v28
	s_waitcnt lgkmcnt(4)
	v_add_f32_e32 v13, v13, v29
	s_waitcnt lgkmcnt(3)
	v_add_f32_e32 v14, v14, v30
	s_waitcnt lgkmcnt(2)
	v_add_f32_e32 v15, v15, v31
	s_waitcnt lgkmcnt(1)
	v_add_f32_e32 v16, v16, v32
	s_waitcnt lgkmcnt(0)
	v_add_f32_e32 v17, v17, v33
	ds_bpermute_b32 v26, v173, v10
	ds_bpermute_b32 v27, v173, v11
	ds_bpermute_b32 v28, v173, v12
	ds_bpermute_b32 v29, v173, v13
	ds_bpermute_b32 v30, v173, v14
	ds_bpermute_b32 v31, v173, v15
	ds_bpermute_b32 v32, v173, v16
	ds_bpermute_b32 v33, v173, v17
	s_waitcnt lgkmcnt(7)
	v_add_f32_e32 v10, v10, v26
	s_waitcnt lgkmcnt(6)
	v_add_f32_e32 v11, v11, v27
	s_waitcnt lgkmcnt(5)
	v_add_f32_e32 v12, v12, v28
	s_waitcnt lgkmcnt(4)
	v_add_f32_e32 v13, v13, v29
	s_waitcnt lgkmcnt(3)
	v_add_f32_e32 v14, v14, v30
	s_waitcnt lgkmcnt(2)
	v_add_f32_e32 v15, v15, v31
	s_waitcnt lgkmcnt(1)
	v_add_f32_e32 v16, v16, v32
	s_waitcnt lgkmcnt(0)
	v_add_f32_e32 v17, v17, v33
	v_cmp_eq_u32_e32 vcc, 0, v174
	s_and_saveexec_b64 s[58:59], vcc
	global_store_dword v167, v2, s[10:11] offset:128
	global_store_dword v167, v3, s[10:11] offset:132
	global_store_dword v167, v4, s[10:11] offset:136
	global_store_dword v167, v5, s[10:11] offset:140
	global_store_dword v167, v6, s[10:11] offset:160
	global_store_dword v167, v7, s[10:11] offset:164
	global_store_dword v167, v8, s[10:11] offset:168
	global_store_dword v167, v9, s[10:11] offset:172
	global_store_dword v167, v10, s[10:11] offset:192
	global_store_dword v167, v11, s[10:11] offset:196
	global_store_dword v167, v12, s[10:11] offset:200
	global_store_dword v167, v13, s[10:11] offset:204
	global_store_dword v167, v14, s[10:11] offset:224
	global_store_dword v167, v15, s[10:11] offset:228
	global_store_dword v167, v16, s[10:11] offset:232
	global_store_dword v167, v17, s[10:11] offset:236
	s_mov_b64 exec, -1
	s_add_u32 s10, s10, 0x18000
	s_addc_u32 s11, s11, 0
	s_waitcnt vmcnt(46)
	v_mul_f32_e32 v175, 0.5, v175
	v_mul_f32_e32 v176, 0.5, v176
	s_waitcnt vmcnt(46)
	v_fmac_f32_e32 v34, v66, v175
	v_fmac_f32_e32 v50, v82, v176
	global_store_dword v162, v34, s[48:49]
	global_store_dword v162, v50, s[48:49] offset:128
	s_waitcnt vmcnt(46)
	v_fmac_f32_e32 v35, v67, v175
	v_fmac_f32_e32 v51, v83, v176
	global_store_dword v163, v35, s[48:49]
	global_store_dword v163, v51, s[48:49] offset:128
	s_waitcnt vmcnt(46)
	v_fmac_f32_e32 v36, v68, v175
	v_fmac_f32_e32 v52, v84, v176
	global_store_dword v164, v36, s[48:49]
	global_store_dword v164, v52, s[48:49] offset:128
	s_waitcnt vmcnt(46)
	v_fmac_f32_e32 v37, v69, v175
	v_fmac_f32_e32 v53, v85, v176
	global_store_dword v165, v37, s[48:49]
	global_store_dword v165, v53, s[48:49] offset:128
	s_add_u32 s48, s48, 0x8000
	s_addc_u32 s49, s49, 0
	s_waitcnt vmcnt(46)
	v_fmac_f32_e32 v38, v70, v175
	v_fmac_f32_e32 v54, v86, v176
	global_store_dword v162, v38, s[48:49]
	global_store_dword v162, v54, s[48:49] offset:128
	s_waitcnt vmcnt(46)
	v_fmac_f32_e32 v39, v71, v175
	v_fmac_f32_e32 v55, v87, v176
	global_store_dword v163, v39, s[48:49]
	global_store_dword v163, v55, s[48:49] offset:128
	s_waitcnt vmcnt(46)
	v_fmac_f32_e32 v40, v72, v175
	v_fmac_f32_e32 v56, v88, v176
	global_store_dword v164, v40, s[48:49]
	global_store_dword v164, v56, s[48:49] offset:128
	s_waitcnt vmcnt(46)
	v_fmac_f32_e32 v41, v73, v175
	v_fmac_f32_e32 v57, v89, v176
	global_store_dword v165, v41, s[48:49]
	global_store_dword v165, v57, s[48:49] offset:128
	s_add_u32 s48, s48, 0x8000
	s_addc_u32 s49, s49, 0
	s_waitcnt vmcnt(46)
	v_fmac_f32_e32 v42, v74, v175
	v_fmac_f32_e32 v58, v90, v176
	global_store_dword v162, v42, s[48:49]
	global_store_dword v162, v58, s[48:49] offset:128
	s_waitcnt vmcnt(46)
	v_fmac_f32_e32 v43, v75, v175
	v_fmac_f32_e32 v59, v91, v176
	global_store_dword v163, v43, s[48:49]
	global_store_dword v163, v59, s[48:49] offset:128
	s_waitcnt vmcnt(46)
	v_fmac_f32_e32 v44, v76, v175
	v_fmac_f32_e32 v60, v92, v176
	global_store_dword v164, v44, s[48:49]
	global_store_dword v164, v60, s[48:49] offset:128
	s_waitcnt vmcnt(46)
	v_fmac_f32_e32 v45, v77, v175
	v_fmac_f32_e32 v61, v93, v176
	global_store_dword v165, v45, s[48:49]
	global_store_dword v165, v61, s[48:49] offset:128
	s_add_u32 s48, s48, 0x8000
	s_addc_u32 s49, s49, 0
	s_waitcnt vmcnt(46)
	v_fmac_f32_e32 v46, v78, v175
	v_fmac_f32_e32 v62, v94, v176
	global_store_dword v162, v46, s[48:49]
	global_store_dword v162, v62, s[48:49] offset:128
	s_waitcnt vmcnt(46)
	v_fmac_f32_e32 v47, v79, v175
	v_fmac_f32_e32 v63, v95, v176
	global_store_dword v163, v47, s[48:49]
	global_store_dword v163, v63, s[48:49] offset:128
	s_waitcnt vmcnt(46)
	v_fmac_f32_e32 v48, v80, v175
	v_fmac_f32_e32 v64, v96, v176
	global_store_dword v164, v48, s[48:49]
	global_store_dword v164, v64, s[48:49] offset:128
	s_waitcnt vmcnt(46)
	v_fmac_f32_e32 v49, v81, v175
	v_fmac_f32_e32 v65, v97, v176
	global_store_dword v165, v49, s[48:49]
	global_store_dword v165, v65, s[48:49] offset:128
	s_sub_u32 s48, s48, 0x18000
	s_subb_u32 s49, s49, 0
	s_add_u32 s48, s48, 0x20000
	s_addc_u32 s49, s49, 0
	global_load_dword v66, v162, s[48:49]
	global_load_dword v82, v162, s[48:49] offset:128
	global_load_dword v67, v163, s[48:49]
	global_load_dword v83, v163, s[48:49] offset:128
	global_load_dword v68, v164, s[48:49]
	global_load_dword v84, v164, s[48:49] offset:128
	global_load_dword v69, v165, s[48:49]
	global_load_dword v85, v165, s[48:49] offset:128
	s_add_u32 s48, s48, 0x8000
	s_addc_u32 s49, s49, 0
	global_load_dword v70, v162, s[48:49]
	global_load_dword v86, v162, s[48:49] offset:128
	global_load_dword v71, v163, s[48:49]
	global_load_dword v87, v163, s[48:49] offset:128
	global_load_dword v72, v164, s[48:49]
	global_load_dword v88, v164, s[48:49] offset:128
	global_load_dword v73, v165, s[48:49]
	global_load_dword v89, v165, s[48:49] offset:128
	s_add_u32 s48, s48, 0x8000
	s_addc_u32 s49, s49, 0
	global_load_dword v74, v162, s[48:49]
	global_load_dword v90, v162, s[48:49] offset:128
	global_load_dword v75, v163, s[48:49]
	global_load_dword v91, v163, s[48:49] offset:128
	global_load_dword v76, v164, s[48:49]
	global_load_dword v92, v164, s[48:49] offset:128
	global_load_dword v77, v165, s[48:49]
	global_load_dword v93, v165, s[48:49] offset:128
	s_add_u32 s48, s48, 0x8000
	s_addc_u32 s49, s49, 0
	global_load_dword v78, v162, s[48:49]
	global_load_dword v94, v162, s[48:49] offset:128
	global_load_dword v79, v163, s[48:49]
	global_load_dword v95, v163, s[48:49] offset:128
	global_load_dword v80, v164, s[48:49]
	global_load_dword v96, v164, s[48:49] offset:128
	global_load_dword v81, v165, s[48:49]
	global_load_dword v97, v165, s[48:49] offset:128
	s_sub_u32 s48, s48, 0x18000
	s_subb_u32 s49, s49, 0
	v_mul_f32_e32 v34, v34, v34
	v_fmac_f32_e32 v34, v50, v50
	v_mul_f32_e32 v35, v35, v35
	v_fmac_f32_e32 v35, v51, v51
	v_mul_f32_e32 v36, v36, v36
	v_fmac_f32_e32 v36, v52, v52
	v_mul_f32_e32 v37, v37, v37
	v_fmac_f32_e32 v37, v53, v53
	v_mul_f32_e32 v38, v38, v38
	v_fmac_f32_e32 v38, v54, v54
	v_mul_f32_e32 v39, v39, v39
	v_fmac_f32_e32 v39, v55, v55
	v_mul_f32_e32 v40, v40, v40
	v_fmac_f32_e32 v40, v56, v56
	v_mul_f32_e32 v41, v41, v41
	v_fmac_f32_e32 v41, v57, v57
	v_mul_f32_e32 v42, v42, v42
	v_fmac_f32_e32 v42, v58, v58
	v_mul_f32_e32 v43, v43, v43
	v_fmac_f32_e32 v43, v59, v59
	v_mul_f32_e32 v44, v44, v44
	v_fmac_f32_e32 v44, v60, v60
	v_mul_f32_e32 v45, v45, v45
	v_fmac_f32_e32 v45, v61, v61
	v_mul_f32_e32 v46, v46, v46
	v_fmac_f32_e32 v46, v62, v62
	v_mul_f32_e32 v47, v47, v47
	v_fmac_f32_e32 v47, v63, v63
	v_mul_f32_e32 v48, v48, v48
	v_fmac_f32_e32 v48, v64, v64
	v_mul_f32_e32 v49, v49, v49
	v_fmac_f32_e32 v49, v65, v65
	s_waitcnt lgkmcnt(0)
	ds_bpermute_b32 v50, v168, v34
	ds_bpermute_b32 v51, v168, v35
	ds_bpermute_b32 v52, v168, v36
	ds_bpermute_b32 v53, v168, v37
	ds_bpermute_b32 v54, v168, v38
	ds_bpermute_b32 v55, v168, v39
	ds_bpermute_b32 v56, v168, v40
	ds_bpermute_b32 v57, v168, v41
	s_waitcnt lgkmcnt(7)
	v_add_f32_e32 v34, v34, v50
	s_waitcnt lgkmcnt(6)
	v_add_f32_e32 v35, v35, v51
	s_waitcnt lgkmcnt(5)
	v_add_f32_e32 v36, v36, v52
	s_waitcnt lgkmcnt(4)
	v_add_f32_e32 v37, v37, v53
	s_waitcnt lgkmcnt(3)
	v_add_f32_e32 v38, v38, v54
	s_waitcnt lgkmcnt(2)
	v_add_f32_e32 v39, v39, v55
	s_waitcnt lgkmcnt(1)
	v_add_f32_e32 v40, v40, v56
	s_waitcnt lgkmcnt(0)
	v_add_f32_e32 v41, v41, v57
	ds_bpermute_b32 v50, v169, v34
	ds_bpermute_b32 v51, v169, v35
	ds_bpermute_b32 v52, v169, v36
	ds_bpermute_b32 v53, v169, v37
	ds_bpermute_b32 v54, v169, v38
	ds_bpermute_b32 v55, v169, v39
	ds_bpermute_b32 v56, v169, v40
	ds_bpermute_b32 v57, v169, v41
	s_waitcnt lgkmcnt(7)
	v_add_f32_e32 v34, v34, v50
	s_waitcnt lgkmcnt(6)
	v_add_f32_e32 v35, v35, v51
	s_waitcnt lgkmcnt(5)
	v_add_f32_e32 v36, v36, v52
	s_waitcnt lgkmcnt(4)
	v_add_f32_e32 v37, v37, v53
	s_waitcnt lgkmcnt(3)
	v_add_f32_e32 v38, v38, v54
	s_waitcnt lgkmcnt(2)
	v_add_f32_e32 v39, v39, v55
	s_waitcnt lgkmcnt(1)
	v_add_f32_e32 v40, v40, v56
	s_waitcnt lgkmcnt(0)
	v_add_f32_e32 v41, v41, v57
	ds_bpermute_b32 v50, v171, v34
	ds_bpermute_b32 v51, v171, v35
	ds_bpermute_b32 v52, v171, v36
	ds_bpermute_b32 v53, v171, v37
	ds_bpermute_b32 v54, v171, v38
	ds_bpermute_b32 v55, v171, v39
	ds_bpermute_b32 v56, v171, v40
	ds_bpermute_b32 v57, v171, v41
	s_waitcnt lgkmcnt(7)
	v_add_f32_e32 v34, v34, v50
	s_waitcnt lgkmcnt(6)
	v_add_f32_e32 v35, v35, v51
	s_waitcnt lgkmcnt(5)
	v_add_f32_e32 v36, v36, v52
	s_waitcnt lgkmcnt(4)
	v_add_f32_e32 v37, v37, v53
	s_waitcnt lgkmcnt(3)
	v_add_f32_e32 v38, v38, v54
	s_waitcnt lgkmcnt(2)
	v_add_f32_e32 v39, v39, v55
	s_waitcnt lgkmcnt(1)
	v_add_f32_e32 v40, v40, v56
	s_waitcnt lgkmcnt(0)
	v_add_f32_e32 v41, v41, v57
	ds_bpermute_b32 v50, v172, v34
	ds_bpermute_b32 v51, v172, v35
	ds_bpermute_b32 v52, v172, v36
	ds_bpermute_b32 v53, v172, v37
	ds_bpermute_b32 v54, v172, v38
	ds_bpermute_b32 v55, v172, v39
	ds_bpermute_b32 v56, v172, v40
	ds_bpermute_b32 v57, v172, v41
	s_waitcnt lgkmcnt(7)
	v_add_f32_e32 v34, v34, v50
	s_waitcnt lgkmcnt(6)
	v_add_f32_e32 v35, v35, v51
	s_waitcnt lgkmcnt(5)
	v_add_f32_e32 v36, v36, v52
	s_waitcnt lgkmcnt(4)
	v_add_f32_e32 v37, v37, v53
	s_waitcnt lgkmcnt(3)
	v_add_f32_e32 v38, v38, v54
	s_waitcnt lgkmcnt(2)
	v_add_f32_e32 v39, v39, v55
	s_waitcnt lgkmcnt(1)
	v_add_f32_e32 v40, v40, v56
	s_waitcnt lgkmcnt(0)
	v_add_f32_e32 v41, v41, v57
	ds_bpermute_b32 v50, v173, v34
	ds_bpermute_b32 v51, v173, v35
	ds_bpermute_b32 v52, v173, v36
	ds_bpermute_b32 v53, v173, v37
	ds_bpermute_b32 v54, v173, v38
	ds_bpermute_b32 v55, v173, v39
	ds_bpermute_b32 v56, v173, v40
	ds_bpermute_b32 v57, v173, v41
	s_waitcnt lgkmcnt(7)
	v_add_f32_e32 v34, v34, v50
	s_waitcnt lgkmcnt(6)
	v_add_f32_e32 v35, v35, v51
	s_waitcnt lgkmcnt(5)
	v_add_f32_e32 v36, v36, v52
	s_waitcnt lgkmcnt(4)
	v_add_f32_e32 v37, v37, v53
	s_waitcnt lgkmcnt(3)
	v_add_f32_e32 v38, v38, v54
	s_waitcnt lgkmcnt(2)
	v_add_f32_e32 v39, v39, v55
	s_waitcnt lgkmcnt(1)
	v_add_f32_e32 v40, v40, v56
	s_waitcnt lgkmcnt(0)
	v_add_f32_e32 v41, v41, v57
	ds_bpermute_b32 v58, v168, v42
	ds_bpermute_b32 v59, v168, v43
	ds_bpermute_b32 v60, v168, v44
	ds_bpermute_b32 v61, v168, v45
	ds_bpermute_b32 v62, v168, v46
	ds_bpermute_b32 v63, v168, v47
	ds_bpermute_b32 v64, v168, v48
	ds_bpermute_b32 v65, v168, v49
	s_waitcnt lgkmcnt(7)
	v_add_f32_e32 v42, v42, v58
	s_waitcnt lgkmcnt(6)
	v_add_f32_e32 v43, v43, v59
	s_waitcnt lgkmcnt(5)
	v_add_f32_e32 v44, v44, v60
	s_waitcnt lgkmcnt(4)
	v_add_f32_e32 v45, v45, v61
	s_waitcnt lgkmcnt(3)
	v_add_f32_e32 v46, v46, v62
	s_waitcnt lgkmcnt(2)
	v_add_f32_e32 v47, v47, v63
	s_waitcnt lgkmcnt(1)
	v_add_f32_e32 v48, v48, v64
	s_waitcnt lgkmcnt(0)
	v_add_f32_e32 v49, v49, v65
	ds_bpermute_b32 v58, v169, v42
	ds_bpermute_b32 v59, v169, v43
	ds_bpermute_b32 v60, v169, v44
	ds_bpermute_b32 v61, v169, v45
	ds_bpermute_b32 v62, v169, v46
	ds_bpermute_b32 v63, v169, v47
	ds_bpermute_b32 v64, v169, v48
	ds_bpermute_b32 v65, v169, v49
	s_waitcnt lgkmcnt(7)
	v_add_f32_e32 v42, v42, v58
	s_waitcnt lgkmcnt(6)
	v_add_f32_e32 v43, v43, v59
	s_waitcnt lgkmcnt(5)
	v_add_f32_e32 v44, v44, v60
	s_waitcnt lgkmcnt(4)
	v_add_f32_e32 v45, v45, v61
	s_waitcnt lgkmcnt(3)
	v_add_f32_e32 v46, v46, v62
	s_waitcnt lgkmcnt(2)
	v_add_f32_e32 v47, v47, v63
	s_waitcnt lgkmcnt(1)
	v_add_f32_e32 v48, v48, v64
	s_waitcnt lgkmcnt(0)
	v_add_f32_e32 v49, v49, v65
	ds_bpermute_b32 v58, v171, v42
	ds_bpermute_b32 v59, v171, v43
	ds_bpermute_b32 v60, v171, v44
	ds_bpermute_b32 v61, v171, v45
	ds_bpermute_b32 v62, v171, v46
	ds_bpermute_b32 v63, v171, v47
	ds_bpermute_b32 v64, v171, v48
	ds_bpermute_b32 v65, v171, v49
	s_waitcnt lgkmcnt(7)
	v_add_f32_e32 v42, v42, v58
	s_waitcnt lgkmcnt(6)
	v_add_f32_e32 v43, v43, v59
	s_waitcnt lgkmcnt(5)
	v_add_f32_e32 v44, v44, v60
	s_waitcnt lgkmcnt(4)
	v_add_f32_e32 v45, v45, v61
	s_waitcnt lgkmcnt(3)
	v_add_f32_e32 v46, v46, v62
	s_waitcnt lgkmcnt(2)
	v_add_f32_e32 v47, v47, v63
	s_waitcnt lgkmcnt(1)
	v_add_f32_e32 v48, v48, v64
	s_waitcnt lgkmcnt(0)
	v_add_f32_e32 v49, v49, v65
	ds_bpermute_b32 v58, v172, v42
	ds_bpermute_b32 v59, v172, v43
	ds_bpermute_b32 v60, v172, v44
	ds_bpermute_b32 v61, v172, v45
	ds_bpermute_b32 v62, v172, v46
	ds_bpermute_b32 v63, v172, v47
	ds_bpermute_b32 v64, v172, v48
	ds_bpermute_b32 v65, v172, v49
	s_waitcnt lgkmcnt(7)
	v_add_f32_e32 v42, v42, v58
	s_waitcnt lgkmcnt(6)
	v_add_f32_e32 v43, v43, v59
	s_waitcnt lgkmcnt(5)
	v_add_f32_e32 v44, v44, v60
	s_waitcnt lgkmcnt(4)
	v_add_f32_e32 v45, v45, v61
	s_waitcnt lgkmcnt(3)
	v_add_f32_e32 v46, v46, v62
	s_waitcnt lgkmcnt(2)
	v_add_f32_e32 v47, v47, v63
	s_waitcnt lgkmcnt(1)
	v_add_f32_e32 v48, v48, v64
	s_waitcnt lgkmcnt(0)
	v_add_f32_e32 v49, v49, v65
	ds_bpermute_b32 v58, v173, v42
	ds_bpermute_b32 v59, v173, v43
	ds_bpermute_b32 v60, v173, v44
	ds_bpermute_b32 v61, v173, v45
	ds_bpermute_b32 v62, v173, v46
	ds_bpermute_b32 v63, v173, v47
	ds_bpermute_b32 v64, v173, v48
	ds_bpermute_b32 v65, v173, v49
	s_waitcnt lgkmcnt(7)
	v_add_f32_e32 v42, v42, v58
	s_waitcnt lgkmcnt(6)
	v_add_f32_e32 v43, v43, v59
	s_waitcnt lgkmcnt(5)
	v_add_f32_e32 v44, v44, v60
	s_waitcnt lgkmcnt(4)
	v_add_f32_e32 v45, v45, v61
	s_waitcnt lgkmcnt(3)
	v_add_f32_e32 v46, v46, v62
	s_waitcnt lgkmcnt(2)
	v_add_f32_e32 v47, v47, v63
	s_waitcnt lgkmcnt(1)
	v_add_f32_e32 v48, v48, v64
	s_waitcnt lgkmcnt(0)
	v_add_f32_e32 v49, v49, v65
	v_cmp_eq_u32_e32 vcc, 0, v174
	s_and_saveexec_b64 s[58:59], vcc
	global_store_dword v167, v34, s[10:11]
	global_store_dword v167, v35, s[10:11] offset:4
	global_store_dword v167, v36, s[10:11] offset:8
	global_store_dword v167, v37, s[10:11] offset:12
	global_store_dword v167, v38, s[10:11] offset:32
	global_store_dword v167, v39, s[10:11] offset:36
	global_store_dword v167, v40, s[10:11] offset:40
	global_store_dword v167, v41, s[10:11] offset:44
	global_store_dword v167, v42, s[10:11] offset:64
	global_store_dword v167, v43, s[10:11] offset:68
	global_store_dword v167, v44, s[10:11] offset:72
	global_store_dword v167, v45, s[10:11] offset:76
	global_store_dword v167, v46, s[10:11] offset:96
	global_store_dword v167, v47, s[10:11] offset:100
	global_store_dword v167, v48, s[10:11] offset:104
	global_store_dword v167, v49, s[10:11] offset:108
	s_mov_b64 exec, -1
	s_waitcnt vmcnt(46)
	v_fmac_f32_e32 v66, v98, v175
	v_fmac_f32_e32 v82, v114, v176
	global_store_dword v162, v66, s[48:49]
	global_store_dword v162, v82, s[48:49] offset:128
	s_waitcnt vmcnt(46)
	v_fmac_f32_e32 v67, v99, v175
	v_fmac_f32_e32 v83, v115, v176
	global_store_dword v163, v67, s[48:49]
	global_store_dword v163, v83, s[48:49] offset:128
	s_waitcnt vmcnt(46)
	v_fmac_f32_e32 v68, v100, v175
	v_fmac_f32_e32 v84, v116, v176
	global_store_dword v164, v68, s[48:49]
	global_store_dword v164, v84, s[48:49] offset:128
	s_waitcnt vmcnt(46)
	v_fmac_f32_e32 v69, v101, v175
	v_fmac_f32_e32 v85, v117, v176
	global_store_dword v165, v69, s[48:49]
	global_store_dword v165, v85, s[48:49] offset:128
	s_add_u32 s48, s48, 0x8000
	s_addc_u32 s49, s49, 0
	s_waitcnt vmcnt(46)
	v_fmac_f32_e32 v70, v102, v175
	v_fmac_f32_e32 v86, v118, v176
	global_store_dword v162, v70, s[48:49]
	global_store_dword v162, v86, s[48:49] offset:128
	s_waitcnt vmcnt(46)
	v_fmac_f32_e32 v71, v103, v175
	v_fmac_f32_e32 v87, v119, v176
	global_store_dword v163, v71, s[48:49]
	global_store_dword v163, v87, s[48:49] offset:128
	s_waitcnt vmcnt(46)
	v_fmac_f32_e32 v72, v104, v175
	v_fmac_f32_e32 v88, v120, v176
	global_store_dword v164, v72, s[48:49]
	global_store_dword v164, v88, s[48:49] offset:128
	s_waitcnt vmcnt(46)
	v_fmac_f32_e32 v73, v105, v175
	v_fmac_f32_e32 v89, v121, v176
	global_store_dword v165, v73, s[48:49]
	global_store_dword v165, v89, s[48:49] offset:128
	s_add_u32 s48, s48, 0x8000
	s_addc_u32 s49, s49, 0
	s_waitcnt vmcnt(46)
	v_fmac_f32_e32 v74, v106, v175
	v_fmac_f32_e32 v90, v122, v176
	global_store_dword v162, v74, s[48:49]
	global_store_dword v162, v90, s[48:49] offset:128
	s_waitcnt vmcnt(46)
	v_fmac_f32_e32 v75, v107, v175
	v_fmac_f32_e32 v91, v123, v176
	global_store_dword v163, v75, s[48:49]
	global_store_dword v163, v91, s[48:49] offset:128
	s_waitcnt vmcnt(46)
	v_fmac_f32_e32 v76, v108, v175
	v_fmac_f32_e32 v92, v124, v176
	global_store_dword v164, v76, s[48:49]
	global_store_dword v164, v92, s[48:49] offset:128
	s_waitcnt vmcnt(46)
	v_fmac_f32_e32 v77, v109, v175
	v_fmac_f32_e32 v93, v125, v176
	global_store_dword v165, v77, s[48:49]
	global_store_dword v165, v93, s[48:49] offset:128
	s_add_u32 s48, s48, 0x8000
	s_addc_u32 s49, s49, 0
	s_waitcnt vmcnt(46)
	v_fmac_f32_e32 v78, v110, v175
	v_fmac_f32_e32 v94, v126, v176
	global_store_dword v162, v78, s[48:49]
	global_store_dword v162, v94, s[48:49] offset:128
	s_waitcnt vmcnt(46)
	v_fmac_f32_e32 v79, v111, v175
	v_fmac_f32_e32 v95, v127, v176
	global_store_dword v163, v79, s[48:49]
	global_store_dword v163, v95, s[48:49] offset:128
	s_waitcnt vmcnt(46)
	v_fmac_f32_e32 v80, v112, v175
	v_fmac_f32_e32 v96, v128, v176
	global_store_dword v164, v80, s[48:49]
	global_store_dword v164, v96, s[48:49] offset:128
	s_waitcnt vmcnt(46)
	v_fmac_f32_e32 v81, v113, v175
	v_fmac_f32_e32 v97, v129, v176
	global_store_dword v165, v81, s[48:49]
	global_store_dword v165, v97, s[48:49] offset:128
	s_sub_u32 s48, s48, 0x18000
	s_subb_u32 s49, s49, 0
	v_mul_f32_e32 v66, v66, v66
	v_fmac_f32_e32 v66, v82, v82
	v_mul_f32_e32 v67, v67, v67
	v_fmac_f32_e32 v67, v83, v83
	v_mul_f32_e32 v68, v68, v68
	v_fmac_f32_e32 v68, v84, v84
	v_mul_f32_e32 v69, v69, v69
	v_fmac_f32_e32 v69, v85, v85
	v_mul_f32_e32 v70, v70, v70
	v_fmac_f32_e32 v70, v86, v86
	v_mul_f32_e32 v71, v71, v71
	v_fmac_f32_e32 v71, v87, v87
	v_mul_f32_e32 v72, v72, v72
	v_fmac_f32_e32 v72, v88, v88
	v_mul_f32_e32 v73, v73, v73
	v_fmac_f32_e32 v73, v89, v89
	v_mul_f32_e32 v74, v74, v74
	v_fmac_f32_e32 v74, v90, v90
	v_mul_f32_e32 v75, v75, v75
	v_fmac_f32_e32 v75, v91, v91
	v_mul_f32_e32 v76, v76, v76
	v_fmac_f32_e32 v76, v92, v92
	v_mul_f32_e32 v77, v77, v77
	v_fmac_f32_e32 v77, v93, v93
	v_mul_f32_e32 v78, v78, v78
	v_fmac_f32_e32 v78, v94, v94
	v_mul_f32_e32 v79, v79, v79
	v_fmac_f32_e32 v79, v95, v95
	v_mul_f32_e32 v80, v80, v80
	v_fmac_f32_e32 v80, v96, v96
	v_mul_f32_e32 v81, v81, v81
	v_fmac_f32_e32 v81, v97, v97
	s_waitcnt lgkmcnt(0)
	ds_bpermute_b32 v82, v168, v66
	ds_bpermute_b32 v83, v168, v67
	ds_bpermute_b32 v84, v168, v68
	ds_bpermute_b32 v85, v168, v69
	ds_bpermute_b32 v86, v168, v70
	ds_bpermute_b32 v87, v168, v71
	ds_bpermute_b32 v88, v168, v72
	ds_bpermute_b32 v89, v168, v73
	s_waitcnt lgkmcnt(7)
	v_add_f32_e32 v66, v66, v82
	s_waitcnt lgkmcnt(6)
	v_add_f32_e32 v67, v67, v83
	s_waitcnt lgkmcnt(5)
	v_add_f32_e32 v68, v68, v84
	s_waitcnt lgkmcnt(4)
	v_add_f32_e32 v69, v69, v85
	s_waitcnt lgkmcnt(3)
	v_add_f32_e32 v70, v70, v86
	s_waitcnt lgkmcnt(2)
	v_add_f32_e32 v71, v71, v87
	s_waitcnt lgkmcnt(1)
	v_add_f32_e32 v72, v72, v88
	s_waitcnt lgkmcnt(0)
	v_add_f32_e32 v73, v73, v89
	ds_bpermute_b32 v82, v169, v66
	ds_bpermute_b32 v83, v169, v67
	ds_bpermute_b32 v84, v169, v68
	ds_bpermute_b32 v85, v169, v69
	ds_bpermute_b32 v86, v169, v70
	ds_bpermute_b32 v87, v169, v71
	ds_bpermute_b32 v88, v169, v72
	ds_bpermute_b32 v89, v169, v73
	s_waitcnt lgkmcnt(7)
	v_add_f32_e32 v66, v66, v82
	s_waitcnt lgkmcnt(6)
	v_add_f32_e32 v67, v67, v83
	s_waitcnt lgkmcnt(5)
	v_add_f32_e32 v68, v68, v84
	s_waitcnt lgkmcnt(4)
	v_add_f32_e32 v69, v69, v85
	s_waitcnt lgkmcnt(3)
	v_add_f32_e32 v70, v70, v86
	s_waitcnt lgkmcnt(2)
	v_add_f32_e32 v71, v71, v87
	s_waitcnt lgkmcnt(1)
	v_add_f32_e32 v72, v72, v88
	s_waitcnt lgkmcnt(0)
	v_add_f32_e32 v73, v73, v89
	ds_bpermute_b32 v82, v171, v66
	ds_bpermute_b32 v83, v171, v67
	ds_bpermute_b32 v84, v171, v68
	ds_bpermute_b32 v85, v171, v69
	ds_bpermute_b32 v86, v171, v70
	ds_bpermute_b32 v87, v171, v71
	ds_bpermute_b32 v88, v171, v72
	ds_bpermute_b32 v89, v171, v73
	s_waitcnt lgkmcnt(7)
	v_add_f32_e32 v66, v66, v82
	s_waitcnt lgkmcnt(6)
	v_add_f32_e32 v67, v67, v83
	s_waitcnt lgkmcnt(5)
	v_add_f32_e32 v68, v68, v84
	s_waitcnt lgkmcnt(4)
	v_add_f32_e32 v69, v69, v85
	s_waitcnt lgkmcnt(3)
	v_add_f32_e32 v70, v70, v86
	s_waitcnt lgkmcnt(2)
	v_add_f32_e32 v71, v71, v87
	s_waitcnt lgkmcnt(1)
	v_add_f32_e32 v72, v72, v88
	s_waitcnt lgkmcnt(0)
	v_add_f32_e32 v73, v73, v89
	ds_bpermute_b32 v82, v172, v66
	ds_bpermute_b32 v83, v172, v67
	ds_bpermute_b32 v84, v172, v68
	ds_bpermute_b32 v85, v172, v69
	ds_bpermute_b32 v86, v172, v70
	ds_bpermute_b32 v87, v172, v71
	ds_bpermute_b32 v88, v172, v72
	ds_bpermute_b32 v89, v172, v73
	s_waitcnt lgkmcnt(7)
	v_add_f32_e32 v66, v66, v82
	s_waitcnt lgkmcnt(6)
	v_add_f32_e32 v67, v67, v83
	s_waitcnt lgkmcnt(5)
	v_add_f32_e32 v68, v68, v84
	s_waitcnt lgkmcnt(4)
	v_add_f32_e32 v69, v69, v85
	s_waitcnt lgkmcnt(3)
	v_add_f32_e32 v70, v70, v86
	s_waitcnt lgkmcnt(2)
	v_add_f32_e32 v71, v71, v87
	s_waitcnt lgkmcnt(1)
	v_add_f32_e32 v72, v72, v88
	s_waitcnt lgkmcnt(0)
	v_add_f32_e32 v73, v73, v89
	ds_bpermute_b32 v82, v173, v66
	ds_bpermute_b32 v83, v173, v67
	ds_bpermute_b32 v84, v173, v68
	ds_bpermute_b32 v85, v173, v69
	ds_bpermute_b32 v86, v173, v70
	ds_bpermute_b32 v87, v173, v71
	ds_bpermute_b32 v88, v173, v72
	ds_bpermute_b32 v89, v173, v73
	s_waitcnt lgkmcnt(7)
	v_add_f32_e32 v66, v66, v82
	s_waitcnt lgkmcnt(6)
	v_add_f32_e32 v67, v67, v83
	s_waitcnt lgkmcnt(5)
	v_add_f32_e32 v68, v68, v84
	s_waitcnt lgkmcnt(4)
	v_add_f32_e32 v69, v69, v85
	s_waitcnt lgkmcnt(3)
	v_add_f32_e32 v70, v70, v86
	s_waitcnt lgkmcnt(2)
	v_add_f32_e32 v71, v71, v87
	s_waitcnt lgkmcnt(1)
	v_add_f32_e32 v72, v72, v88
	s_waitcnt lgkmcnt(0)
	v_add_f32_e32 v73, v73, v89
	ds_bpermute_b32 v90, v168, v74
	ds_bpermute_b32 v91, v168, v75
	ds_bpermute_b32 v92, v168, v76
	ds_bpermute_b32 v93, v168, v77
	ds_bpermute_b32 v94, v168, v78
	ds_bpermute_b32 v95, v168, v79
	ds_bpermute_b32 v96, v168, v80
	ds_bpermute_b32 v97, v168, v81
	s_waitcnt lgkmcnt(7)
	v_add_f32_e32 v74, v74, v90
	s_waitcnt lgkmcnt(6)
	v_add_f32_e32 v75, v75, v91
	s_waitcnt lgkmcnt(5)
	v_add_f32_e32 v76, v76, v92
	s_waitcnt lgkmcnt(4)
	v_add_f32_e32 v77, v77, v93
	s_waitcnt lgkmcnt(3)
	v_add_f32_e32 v78, v78, v94
	s_waitcnt lgkmcnt(2)
	v_add_f32_e32 v79, v79, v95
	s_waitcnt lgkmcnt(1)
	v_add_f32_e32 v80, v80, v96
	s_waitcnt lgkmcnt(0)
	v_add_f32_e32 v81, v81, v97
	ds_bpermute_b32 v90, v169, v74
	ds_bpermute_b32 v91, v169, v75
	ds_bpermute_b32 v92, v169, v76
	ds_bpermute_b32 v93, v169, v77
	ds_bpermute_b32 v94, v169, v78
	ds_bpermute_b32 v95, v169, v79
	ds_bpermute_b32 v96, v169, v80
	ds_bpermute_b32 v97, v169, v81
	s_waitcnt lgkmcnt(7)
	v_add_f32_e32 v74, v74, v90
	s_waitcnt lgkmcnt(6)
	v_add_f32_e32 v75, v75, v91
	s_waitcnt lgkmcnt(5)
	v_add_f32_e32 v76, v76, v92
	s_waitcnt lgkmcnt(4)
	v_add_f32_e32 v77, v77, v93
	s_waitcnt lgkmcnt(3)
	v_add_f32_e32 v78, v78, v94
	s_waitcnt lgkmcnt(2)
	v_add_f32_e32 v79, v79, v95
	s_waitcnt lgkmcnt(1)
	v_add_f32_e32 v80, v80, v96
	s_waitcnt lgkmcnt(0)
	v_add_f32_e32 v81, v81, v97
	ds_bpermute_b32 v90, v171, v74
	ds_bpermute_b32 v91, v171, v75
	ds_bpermute_b32 v92, v171, v76
	ds_bpermute_b32 v93, v171, v77
	ds_bpermute_b32 v94, v171, v78
	ds_bpermute_b32 v95, v171, v79
	ds_bpermute_b32 v96, v171, v80
	ds_bpermute_b32 v97, v171, v81
	s_waitcnt lgkmcnt(7)
	v_add_f32_e32 v74, v74, v90
	s_waitcnt lgkmcnt(6)
	v_add_f32_e32 v75, v75, v91
	s_waitcnt lgkmcnt(5)
	v_add_f32_e32 v76, v76, v92
	s_waitcnt lgkmcnt(4)
	v_add_f32_e32 v77, v77, v93
	s_waitcnt lgkmcnt(3)
	v_add_f32_e32 v78, v78, v94
	s_waitcnt lgkmcnt(2)
	v_add_f32_e32 v79, v79, v95
	s_waitcnt lgkmcnt(1)
	v_add_f32_e32 v80, v80, v96
	s_waitcnt lgkmcnt(0)
	v_add_f32_e32 v81, v81, v97
	ds_bpermute_b32 v90, v172, v74
	ds_bpermute_b32 v91, v172, v75
	ds_bpermute_b32 v92, v172, v76
	ds_bpermute_b32 v93, v172, v77
	ds_bpermute_b32 v94, v172, v78
	ds_bpermute_b32 v95, v172, v79
	ds_bpermute_b32 v96, v172, v80
	ds_bpermute_b32 v97, v172, v81
	s_waitcnt lgkmcnt(7)
	v_add_f32_e32 v74, v74, v90
	s_waitcnt lgkmcnt(6)
	v_add_f32_e32 v75, v75, v91
	s_waitcnt lgkmcnt(5)
	v_add_f32_e32 v76, v76, v92
	s_waitcnt lgkmcnt(4)
	v_add_f32_e32 v77, v77, v93
	s_waitcnt lgkmcnt(3)
	v_add_f32_e32 v78, v78, v94
	s_waitcnt lgkmcnt(2)
	v_add_f32_e32 v79, v79, v95
	s_waitcnt lgkmcnt(1)
	v_add_f32_e32 v80, v80, v96
	s_waitcnt lgkmcnt(0)
	v_add_f32_e32 v81, v81, v97
	ds_bpermute_b32 v90, v173, v74
	ds_bpermute_b32 v91, v173, v75
	ds_bpermute_b32 v92, v173, v76
	ds_bpermute_b32 v93, v173, v77
	ds_bpermute_b32 v94, v173, v78
	ds_bpermute_b32 v95, v173, v79
	ds_bpermute_b32 v96, v173, v80
	ds_bpermute_b32 v97, v173, v81
	s_waitcnt lgkmcnt(7)
	v_add_f32_e32 v74, v74, v90
	s_waitcnt lgkmcnt(6)
	v_add_f32_e32 v75, v75, v91
	s_waitcnt lgkmcnt(5)
	v_add_f32_e32 v76, v76, v92
	s_waitcnt lgkmcnt(4)
	v_add_f32_e32 v77, v77, v93
	s_waitcnt lgkmcnt(3)
	v_add_f32_e32 v78, v78, v94
	s_waitcnt lgkmcnt(2)
	v_add_f32_e32 v79, v79, v95
	s_waitcnt lgkmcnt(1)
	v_add_f32_e32 v80, v80, v96
	s_waitcnt lgkmcnt(0)
	v_add_f32_e32 v81, v81, v97
	v_cmp_eq_u32_e32 vcc, 0, v174
	s_and_saveexec_b64 s[58:59], vcc
	global_store_dword v167, v66, s[10:11] offset:128
	global_store_dword v167, v67, s[10:11] offset:132
	global_store_dword v167, v68, s[10:11] offset:136
	global_store_dword v167, v69, s[10:11] offset:140
	global_store_dword v167, v70, s[10:11] offset:160
	global_store_dword v167, v71, s[10:11] offset:164
	global_store_dword v167, v72, s[10:11] offset:168
	global_store_dword v167, v73, s[10:11] offset:172
	global_store_dword v167, v74, s[10:11] offset:192
	global_store_dword v167, v75, s[10:11] offset:196
	global_store_dword v167, v76, s[10:11] offset:200
	global_store_dword v167, v77, s[10:11] offset:204
	global_store_dword v167, v78, s[10:11] offset:224
	global_store_dword v167, v79, s[10:11] offset:228
	global_store_dword v167, v80, s[10:11] offset:232
	global_store_dword v167, v81, s[10:11] offset:236
	s_mov_b64 exec, -1
	v_readlane_b32 s2, v246, 14
	s_nop 0
	s_add_i32 s16, s16, s2
	s_branch .Lhw_ffndown_tloop
